# grid barrier: non-leader workgroups issue their agent-scope L1 invalidate (buffer_inv sc1) at arrival instead of after the release poll (L1 stays empty while the workgroup is parked; leader path uncha
# speedup vs baseline: 1.0017x; 1.0017x over previous
.LBB0_149:
	s_cmp_gt_i32 s67, 1
	s_cbranch_scc0 .LBB0_203
	s_waitcnt vmcnt(0)
	v_readlane_b32 s4, v232, 0
	v_readlane_b32 s5, v232, 1
	s_waitcnt lgkmcnt(0)
	s_barrier
	s_and_saveexec_b64 s[6:7], s[4:5]
	s_cbranch_execz .LBB0_202
	s_add_i32 s3, 0, 0x20000
	v_mov_b32_e32 v0, s3
	s_waitcnt vmcnt(0) expcnt(0) lgkmcnt(0)
	buffer_inv sc1
	ds_read_b32 v2, v0
	s_add_i32 s3, 0, 0x20004
	v_mov_b32_e32 v0, s3
	ds_read_b32 v0, v0
	s_waitcnt lgkmcnt(1)
	v_cmp_ne_u32_e32 vcc, 0, v2
	s_cbranch_vccnz .LBB0_166
	s_add_u32 s8, s68, 0x23718200
	s_addc_u32 s9, s69, 0
	s_add_u32 s10, s68, 0x23718400
	s_addc_u32 s11, s69, 0
	s_add_u32 s12, s68, 0x23718500
	s_addc_u32 s13, s69, 0
	s_add_u32 s14, s68, 0x23718600
	s_addc_u32 s15, s69, 0
	s_add_u32 s16, s68, 0x23718700
	s_addc_u32 s17, s69, 0
	s_add_u32 s18, s68, 0x23718800
	s_addc_u32 s19, s69, 0
	s_add_u32 s20, s68, 0x23718900
	s_addc_u32 s21, s69, 0
	s_add_u32 s22, s68, 0x23718a00
	s_addc_u32 s23, s69, 0
	s_add_u32 s24, s68, 0x23718b00
	s_addc_u32 s25, s69, 0
	s_add_u32 s26, s68, 0x23718c00
	s_addc_u32 s27, s69, 0
	s_add_u32 s28, s68, 0x23718d00
	s_addc_u32 s29, s69, 0
	s_add_u32 s30, s68, 0x23718e00
	s_addc_u32 s31, s69, 0
	s_add_u32 s34, s68, 0x23718f00
	s_addc_u32 s35, s69, 0
	s_add_u32 s36, s68, 0x23719000
	s_load_dword s3, s[0:1], 0x110
	s_addc_u32 s37, s69, 0
	s_add_u32 s38, s68, 0x23719100
	s_addc_u32 s39, s69, 0
	s_add_u32 s40, s68, 0x23719200
	s_addc_u32 s41, s69, 0
	s_waitcnt lgkmcnt(0)
	s_mul_i32 s3, s65, s3
	s_add_u32 s42, s68, 0x23719300
	s_mul_i32 s3, s3, s64
	s_addc_u32 s43, s69, 0
	s_mov_b32 s50, 1
	v_mov_b32_e32 v16, 0
	s_branch .LBB0_154

.LBB0_181:
	s_or_b64 exec, exec, s[12:13]
	s_waitcnt vmcnt(0)
	s_waitcnt vmcnt(0)

.LBB0_209:
	s_or_b64 exec, exec, s[6:7]
	s_cmp_lt_i32 s67, 3
	s_cbranch_scc1 .LBB0_263
	s_waitcnt vmcnt(0)
	v_readlane_b32 s4, v232, 0
	v_readlane_b32 s5, v232, 1
	s_barrier
	s_and_saveexec_b64 s[6:7], s[4:5]
	s_cbranch_execz .LBB0_262
	s_add_i32 s8, 0, 0x20000
	v_mov_b32_e32 v0, s8
	s_waitcnt vmcnt(0) expcnt(0) lgkmcnt(0)
	buffer_inv sc1
	ds_read_b32 v2, v0
	s_add_i32 s8, 0, 0x20004
	v_mov_b32_e32 v0, s8
	ds_read_b32 v0, v0
	s_waitcnt lgkmcnt(1)
	v_cmp_ne_u32_e32 vcc, 0, v2
	s_cbranch_vccnz .LBB0_226
	s_load_dword s4, s[0:1], 0x110
	s_mov_b32 s50, 1
	v_mov_b32_e32 v16, 0
	s_waitcnt lgkmcnt(0)
	s_mul_i32 s8, s65, s4
	s_mul_i32 s3, s8, s3
	s_add_u32 s8, s68, 0x23718200
	s_addc_u32 s9, s69, 0
	s_add_u32 s10, s68, 0x23718400
	s_addc_u32 s11, s69, 0
	s_add_u32 s12, s68, 0x23718500
	s_addc_u32 s13, s69, 0
	s_add_u32 s14, s68, 0x23718600
	s_addc_u32 s15, s69, 0
	s_add_u32 s16, s68, 0x23718700
	s_addc_u32 s17, s69, 0
	s_add_u32 s18, s68, 0x23718800
	s_addc_u32 s19, s69, 0
	s_add_u32 s20, s68, 0x23718900
	s_addc_u32 s21, s69, 0
	s_add_u32 s22, s68, 0x23718a00
	s_addc_u32 s23, s69, 0
	s_add_u32 s24, s68, 0x23718b00
	s_addc_u32 s25, s69, 0
	s_add_u32 s26, s68, 0x23718c00
	s_addc_u32 s27, s69, 0
	s_add_u32 s28, s68, 0x23718d00
	s_addc_u32 s29, s69, 0
	s_add_u32 s30, s68, 0x23718e00
	s_addc_u32 s31, s69, 0
	s_add_u32 s34, s68, 0x23718f00
	s_addc_u32 s35, s69, 0
	s_add_u32 s36, s68, 0x23719000
	s_addc_u32 s37, s69, 0
	s_add_u32 s38, s68, 0x23719100
	s_addc_u32 s39, s69, 0
	s_add_u32 s40, s68, 0x23719200
	s_addc_u32 s41, s69, 0
	s_add_u32 s42, s68, 0x23719300
	s_addc_u32 s43, s69, 0
	s_branch .LBB0_214

.LBB0_284:
	s_cmp_lt_i32 s67, 4
	s_cbranch_scc1 .LBB0_338
	s_waitcnt vmcnt(0)
	v_readlane_b32 s4, v232, 0
	v_readlane_b32 s5, v232, 1
	s_waitcnt vmcnt(0)
	s_barrier
	s_and_saveexec_b64 s[6:7], s[4:5]
	s_cbranch_execz .LBB0_337
	s_add_i32 s8, 0, 0x20000
	v_mov_b32_e32 v0, s8
	s_waitcnt vmcnt(0) expcnt(0) lgkmcnt(0)
	buffer_inv sc1
	ds_read_b32 v2, v0
	s_add_i32 s8, 0, 0x20004
	v_mov_b32_e32 v0, s8
	ds_read_b32 v0, v0
	s_waitcnt lgkmcnt(1)
	v_cmp_ne_u32_e32 vcc, 0, v2
	s_cbranch_vccnz .LBB0_301
	s_load_dword s4, s[0:1], 0x110
	s_mov_b32 s50, 1
	v_mov_b32_e32 v16, 0
	s_waitcnt lgkmcnt(0)
	s_mul_i32 s8, s65, s4
	s_mul_i32 s3, s8, s3
	s_add_u32 s8, s68, 0x23718200
	s_addc_u32 s9, s69, 0
	s_add_u32 s10, s68, 0x23718400
	s_addc_u32 s11, s69, 0
	s_add_u32 s12, s68, 0x23718500
	s_addc_u32 s13, s69, 0
	s_add_u32 s14, s68, 0x23718600
	s_addc_u32 s15, s69, 0
	s_add_u32 s16, s68, 0x23718700
	s_addc_u32 s17, s69, 0
	s_add_u32 s18, s68, 0x23718800
	s_addc_u32 s19, s69, 0
	s_add_u32 s20, s68, 0x23718900
	s_addc_u32 s21, s69, 0
	s_add_u32 s22, s68, 0x23718a00
	s_addc_u32 s23, s69, 0
	s_add_u32 s24, s68, 0x23718b00
	s_addc_u32 s25, s69, 0
	s_add_u32 s26, s68, 0x23718c00
	s_addc_u32 s27, s69, 0
	s_add_u32 s28, s68, 0x23718d00
	s_addc_u32 s29, s69, 0
	s_add_u32 s30, s68, 0x23718e00
	s_addc_u32 s31, s69, 0
	s_add_u32 s34, s68, 0x23718f00
	s_addc_u32 s35, s69, 0
	s_add_u32 s36, s68, 0x23719000
	s_addc_u32 s37, s69, 0
	s_add_u32 s38, s68, 0x23719100
	s_addc_u32 s39, s69, 0
	s_add_u32 s40, s68, 0x23719200
	s_addc_u32 s41, s69, 0
	s_add_u32 s42, s68, 0x23719300
	s_addc_u32 s43, s69, 0
	s_branch .LBB0_289

.LBB0_362:
	s_cmp_lt_i32 s67, 5
	s_cbranch_scc1 .LBB0_416
	s_waitcnt vmcnt(0)
	v_readlane_b32 s4, v232, 0
	v_readlane_b32 s5, v232, 1
	s_waitcnt vmcnt(0)
	s_barrier
	s_and_saveexec_b64 s[6:7], s[4:5]
	s_cbranch_execz .LBB0_415
	s_add_i32 s3, 0, 0x20000
	v_mov_b32_e32 v0, s3
	s_waitcnt vmcnt(0) expcnt(0) lgkmcnt(0)
	buffer_inv sc1
	ds_read_b32 v2, v0
	s_add_i32 s3, 0, 0x20004
	v_mov_b32_e32 v0, s3
	ds_read_b32 v0, v0
	s_waitcnt lgkmcnt(1)
	v_cmp_ne_u32_e32 vcc, 0, v2
	s_cbranch_vccnz .LBB0_379
	s_add_u32 s8, s68, 0x23718200
	s_addc_u32 s9, s69, 0
	s_add_u32 s10, s68, 0x23718400
	s_addc_u32 s11, s69, 0
	s_add_u32 s12, s68, 0x23718500
	s_addc_u32 s13, s69, 0
	s_add_u32 s14, s68, 0x23718600
	s_addc_u32 s15, s69, 0
	s_add_u32 s16, s68, 0x23718700
	s_addc_u32 s17, s69, 0
	s_add_u32 s18, s68, 0x23718800
	s_addc_u32 s19, s69, 0
	s_add_u32 s20, s68, 0x23718900
	s_addc_u32 s21, s69, 0
	s_add_u32 s22, s68, 0x23718a00
	s_addc_u32 s23, s69, 0
	s_add_u32 s24, s68, 0x23718b00
	s_addc_u32 s25, s69, 0
	s_add_u32 s26, s68, 0x23718c00
	s_addc_u32 s27, s69, 0
	s_add_u32 s28, s68, 0x23718d00
	s_addc_u32 s29, s69, 0
	s_add_u32 s30, s68, 0x23718e00
	s_addc_u32 s31, s69, 0
	s_add_u32 s34, s68, 0x23718f00
	s_addc_u32 s35, s69, 0
	s_add_u32 s36, s68, 0x23719000
	s_load_dword s3, s[0:1], 0x110
	s_addc_u32 s37, s69, 0
	s_add_u32 s38, s68, 0x23719100
	s_addc_u32 s39, s69, 0
	s_add_u32 s40, s68, 0x23719200
	s_addc_u32 s41, s69, 0
	s_waitcnt lgkmcnt(0)
	s_mul_i32 s3, s65, s3
	s_add_u32 s42, s68, 0x23719300
	s_mul_i32 s3, s3, s64
	s_addc_u32 s43, s69, 0
	s_mov_b32 s50, 1
	v_mov_b32_e32 v16, 0
	s_branch .LBB0_367

.LBB0_422:
	s_or_b64 exec, exec, s[6:7]
	s_cmp_lt_i32 s67, 6
	s_cbranch_scc1 .LBB0_476
	s_waitcnt vmcnt(0)
	v_readlane_b32 s4, v232, 0
	v_readlane_b32 s5, v232, 1
	s_waitcnt vmcnt(0)
	s_barrier
	s_and_saveexec_b64 s[6:7], s[4:5]
	s_cbranch_execz .LBB0_475
	s_add_i32 s8, 0, 0x20000
	v_mov_b32_e32 v0, s8
	s_waitcnt vmcnt(0) expcnt(0) lgkmcnt(0)
	buffer_inv sc1
	ds_read_b32 v2, v0
	s_add_i32 s8, 0, 0x20004
	v_mov_b32_e32 v0, s8
	ds_read_b32 v0, v0
	s_waitcnt lgkmcnt(1)
	v_cmp_ne_u32_e32 vcc, 0, v2
	s_cbranch_vccnz .LBB0_439
	s_load_dword s4, s[0:1], 0x110
	s_mov_b32 s50, 1
	v_mov_b32_e32 v16, 0
	s_waitcnt lgkmcnt(0)
	s_mul_i32 s8, s65, s4
	s_mul_i32 s3, s8, s3
	s_add_u32 s8, s68, 0x23718200
	s_addc_u32 s9, s69, 0
	s_add_u32 s10, s68, 0x23718400
	s_addc_u32 s11, s69, 0
	s_add_u32 s12, s68, 0x23718500
	s_addc_u32 s13, s69, 0
	s_add_u32 s14, s68, 0x23718600
	s_addc_u32 s15, s69, 0
	s_add_u32 s16, s68, 0x23718700
	s_addc_u32 s17, s69, 0
	s_add_u32 s18, s68, 0x23718800
	s_addc_u32 s19, s69, 0
	s_add_u32 s20, s68, 0x23718900
	s_addc_u32 s21, s69, 0
	s_add_u32 s22, s68, 0x23718a00
	s_addc_u32 s23, s69, 0
	s_add_u32 s24, s68, 0x23718b00
	s_addc_u32 s25, s69, 0
	s_add_u32 s26, s68, 0x23718c00
	s_addc_u32 s27, s69, 0
	s_add_u32 s28, s68, 0x23718d00
	s_addc_u32 s29, s69, 0
	s_add_u32 s30, s68, 0x23718e00
	s_addc_u32 s31, s69, 0
	s_add_u32 s34, s68, 0x23718f00
	s_addc_u32 s35, s69, 0
	s_add_u32 s36, s68, 0x23719000
	s_addc_u32 s37, s69, 0
	s_add_u32 s38, s68, 0x23719100
	s_addc_u32 s39, s69, 0
	s_add_u32 s40, s68, 0x23719200
	s_addc_u32 s41, s69, 0
	s_add_u32 s42, s68, 0x23719300
	s_addc_u32 s43, s69, 0
	s_branch .LBB0_427

.LBB0_501:
	s_cmp_lt_i32 s67, 7
	s_cbranch_scc1 .LBB0_555
	s_waitcnt vmcnt(0)
	v_readlane_b32 s4, v232, 0
	v_readlane_b32 s5, v232, 1
	s_waitcnt vmcnt(0) lgkmcnt(0)
	s_barrier
	s_and_saveexec_b64 s[6:7], s[4:5]
	s_cbranch_execz .LBB0_554
	s_add_i32 s3, 0, 0x20000
	v_mov_b32_e32 v0, s3
	s_waitcnt vmcnt(0) expcnt(0) lgkmcnt(0)
	buffer_inv sc1
	ds_read_b32 v2, v0
	s_add_i32 s3, 0, 0x20004
	v_mov_b32_e32 v0, s3
	ds_read_b32 v0, v0
	s_waitcnt lgkmcnt(1)
	v_cmp_ne_u32_e32 vcc, 0, v2
	s_cbranch_vccnz .LBB0_518
	s_add_u32 s8, s68, 0x23718200
	s_addc_u32 s9, s69, 0
	s_add_u32 s10, s68, 0x23718400
	s_addc_u32 s11, s69, 0
	s_add_u32 s12, s68, 0x23718500
	s_addc_u32 s13, s69, 0
	s_add_u32 s14, s68, 0x23718600
	s_addc_u32 s15, s69, 0
	s_add_u32 s16, s68, 0x23718700
	s_addc_u32 s17, s69, 0
	s_add_u32 s18, s68, 0x23718800
	s_addc_u32 s19, s69, 0
	s_add_u32 s20, s68, 0x23718900
	s_addc_u32 s21, s69, 0
	s_add_u32 s22, s68, 0x23718a00
	s_addc_u32 s23, s69, 0
	s_add_u32 s24, s68, 0x23718b00
	s_addc_u32 s25, s69, 0
	s_add_u32 s26, s68, 0x23718c00
	s_addc_u32 s27, s69, 0
	s_add_u32 s28, s68, 0x23718d00
	s_addc_u32 s29, s69, 0
	s_add_u32 s30, s68, 0x23718e00
	s_addc_u32 s31, s69, 0
	s_add_u32 s34, s68, 0x23718f00
	s_addc_u32 s35, s69, 0
	s_add_u32 s36, s68, 0x23719000
	s_load_dword s3, s[0:1], 0x110
	s_addc_u32 s37, s69, 0
	s_add_u32 s38, s68, 0x23719100
	s_addc_u32 s39, s69, 0
	s_add_u32 s40, s68, 0x23719200
	s_addc_u32 s41, s69, 0
	s_waitcnt lgkmcnt(0)
	s_mul_i32 s3, s65, s3
	s_add_u32 s42, s68, 0x23719300
	s_mul_i32 s3, s3, s64
	s_addc_u32 s43, s69, 0
	s_mov_b32 s50, 1
	v_mov_b32_e32 v16, 0
	s_branch .LBB0_506

.LBB0_563:
	s_or_b64 exec, exec, s[14:15]
	s_cmp_lt_i32 s67, 8
	s_cbranch_scc1 .LBB0_617
	s_waitcnt vmcnt(0)
	v_readlane_b32 s4, v232, 0
	v_readlane_b32 s5, v232, 1
	s_waitcnt vmcnt(0) lgkmcnt(0)
	s_barrier
	s_and_saveexec_b64 s[6:7], s[4:5]
	s_cbranch_execz .LBB0_616
	s_add_i32 s3, 0, 0x20000
	v_mov_b32_e32 v0, s3
	s_waitcnt vmcnt(0) expcnt(0) lgkmcnt(0)
	buffer_inv sc1
	ds_read_b32 v2, v0
	s_add_i32 s3, 0, 0x20004
	v_mov_b32_e32 v0, s3
	ds_read_b32 v0, v0
	s_waitcnt lgkmcnt(1)
	v_cmp_ne_u32_e32 vcc, 0, v2
	s_cbranch_vccnz .LBB0_580
	s_add_u32 s8, s68, 0x23718200
	s_addc_u32 s9, s69, 0
	s_add_u32 s10, s68, 0x23718400
	s_addc_u32 s11, s69, 0
	s_add_u32 s12, s68, 0x23718500
	s_addc_u32 s13, s69, 0
	s_add_u32 s14, s68, 0x23718600
	s_addc_u32 s15, s69, 0
	s_add_u32 s16, s68, 0x23718700
	s_addc_u32 s17, s69, 0
	s_add_u32 s18, s68, 0x23718800
	s_addc_u32 s19, s69, 0
	s_add_u32 s20, s68, 0x23718900
	s_addc_u32 s21, s69, 0
	s_add_u32 s22, s68, 0x23718a00
	s_addc_u32 s23, s69, 0
	s_add_u32 s24, s68, 0x23718b00
	s_addc_u32 s25, s69, 0
	s_add_u32 s26, s68, 0x23718c00
	s_addc_u32 s27, s69, 0
	s_add_u32 s28, s68, 0x23718d00
	s_addc_u32 s29, s69, 0
	s_add_u32 s30, s68, 0x23718e00
	s_addc_u32 s31, s69, 0
	s_add_u32 s34, s68, 0x23718f00
	s_addc_u32 s35, s69, 0
	s_add_u32 s36, s68, 0x23719000
	s_load_dword s3, s[0:1], 0x110
	s_addc_u32 s37, s69, 0
	s_add_u32 s38, s68, 0x23719100
	s_addc_u32 s39, s69, 0
	s_add_u32 s40, s68, 0x23719200
	s_addc_u32 s41, s69, 0
	s_waitcnt lgkmcnt(0)
	s_mul_i32 s3, s65, s3
	s_add_u32 s42, s68, 0x23719300
	s_mul_i32 s3, s3, s64
	s_addc_u32 s43, s69, 0
	s_mov_b32 s50, 1
	v_mov_b32_e32 v16, 0
	s_branch .LBB0_568

.LBB0_694:
	s_cmp_lt_i32 s67, 9
	s_cbranch_scc1 .LBB0_748
	s_waitcnt vmcnt(0)
	v_readlane_b32 s4, v232, 0
	v_readlane_b32 s5, v232, 1
	s_waitcnt vmcnt(0)
	s_barrier
	s_and_saveexec_b64 s[6:7], s[4:5]
	s_cbranch_execz .LBB0_747
	s_add_i32 s3, 0, 0x20000
	v_mov_b32_e32 v0, s3
	s_waitcnt vmcnt(0) expcnt(0) lgkmcnt(0)
	buffer_inv sc1
	ds_read_b32 v2, v0
	s_add_i32 s3, 0, 0x20004
	v_mov_b32_e32 v0, s3
	ds_read_b32 v0, v0
	s_waitcnt lgkmcnt(1)
	v_cmp_ne_u32_e32 vcc, 0, v2
	s_cbranch_vccnz .LBB0_711
	s_add_u32 s8, s68, 0x23718200
	s_addc_u32 s9, s69, 0
	s_add_u32 s10, s68, 0x23718400
	s_addc_u32 s11, s69, 0
	s_add_u32 s12, s68, 0x23718500
	s_addc_u32 s13, s69, 0
	s_add_u32 s14, s68, 0x23718600
	s_addc_u32 s15, s69, 0
	s_add_u32 s16, s68, 0x23718700
	s_addc_u32 s17, s69, 0
	s_add_u32 s18, s68, 0x23718800
	s_addc_u32 s19, s69, 0
	s_add_u32 s20, s68, 0x23718900
	s_addc_u32 s21, s69, 0
	s_add_u32 s22, s68, 0x23718a00
	s_addc_u32 s23, s69, 0
	s_add_u32 s24, s68, 0x23718b00
	s_addc_u32 s25, s69, 0
	s_add_u32 s26, s68, 0x23718c00
	s_addc_u32 s27, s69, 0
	s_add_u32 s28, s68, 0x23718d00
	s_addc_u32 s29, s69, 0
	s_add_u32 s30, s68, 0x23718e00
	s_addc_u32 s31, s69, 0
	s_add_u32 s34, s68, 0x23718f00
	s_addc_u32 s35, s69, 0
	s_add_u32 s36, s68, 0x23719000
	s_load_dword s3, s[0:1], 0x110
	s_addc_u32 s37, s69, 0
	s_add_u32 s38, s68, 0x23719100
	s_addc_u32 s39, s69, 0
	s_add_u32 s40, s68, 0x23719200
	s_addc_u32 s41, s69, 0
	s_waitcnt lgkmcnt(0)
	s_mul_i32 s3, s65, s3
	s_add_u32 s42, s68, 0x23719300
	s_mul_i32 s3, s3, s64
	s_addc_u32 s43, s69, 0
	s_mov_b32 s50, 1
	v_mov_b32_e32 v16, 0
	s_branch .LBB0_699

.LBB0_754:
	s_or_b64 exec, exec, s[36:37]
	s_cmp_lt_i32 s67, 10
	s_cbranch_scc1 .LBB0_808
	s_waitcnt vmcnt(0)
	v_readlane_b32 s4, v232, 0
	v_readlane_b32 s5, v232, 1
	s_waitcnt vmcnt(0) lgkmcnt(0)
	s_barrier
	s_and_saveexec_b64 s[6:7], s[4:5]
	s_cbranch_execz .LBB0_807
	s_add_i32 s3, 0, 0x20000
	v_mov_b32_e32 v0, s3
	s_waitcnt vmcnt(0) expcnt(0) lgkmcnt(0)
	buffer_inv sc1
	ds_read_b32 v2, v0
	s_add_i32 s3, 0, 0x20004
	v_mov_b32_e32 v0, s3
	ds_read_b32 v0, v0
	s_waitcnt lgkmcnt(1)
	v_cmp_ne_u32_e32 vcc, 0, v2
	s_cbranch_vccnz .LBB0_771
	s_add_u32 s8, s68, 0x23718200
	s_addc_u32 s9, s69, 0
	s_add_u32 s10, s68, 0x23718400
	s_addc_u32 s11, s69, 0
	s_add_u32 s12, s68, 0x23718500
	s_addc_u32 s13, s69, 0
	s_add_u32 s14, s68, 0x23718600
	s_addc_u32 s15, s69, 0
	s_add_u32 s16, s68, 0x23718700
	s_addc_u32 s17, s69, 0
	s_add_u32 s18, s68, 0x23718800
	s_addc_u32 s19, s69, 0
	s_add_u32 s20, s68, 0x23718900
	s_addc_u32 s21, s69, 0
	s_add_u32 s22, s68, 0x23718a00
	s_addc_u32 s23, s69, 0
	s_add_u32 s24, s68, 0x23718b00
	s_addc_u32 s25, s69, 0
	s_add_u32 s26, s68, 0x23718c00
	s_addc_u32 s27, s69, 0
	s_add_u32 s28, s68, 0x23718d00
	s_addc_u32 s29, s69, 0
	s_add_u32 s30, s68, 0x23718e00
	s_addc_u32 s31, s69, 0
	s_add_u32 s34, s68, 0x23718f00
	s_addc_u32 s35, s69, 0
	s_add_u32 s36, s68, 0x23719000
	s_load_dword s3, s[0:1], 0x110
	s_addc_u32 s37, s69, 0
	s_add_u32 s38, s68, 0x23719100
	s_addc_u32 s39, s69, 0
	s_add_u32 s40, s68, 0x23719200
	s_addc_u32 s41, s69, 0
	s_waitcnt lgkmcnt(0)
	s_mul_i32 s3, s65, s3
	s_add_u32 s42, s68, 0x23719300
	s_mul_i32 s3, s3, s64
	s_addc_u32 s43, s69, 0
	s_mov_b32 s50, 1
	v_mov_b32_e32 v16, 0
	s_branch .LBB0_759

.LBB0_885:
	s_cmp_lt_i32 s67, 11
	s_cbranch_scc1 .LBB0_939
	s_waitcnt vmcnt(0)
	v_readlane_b32 s4, v232, 0
	v_readlane_b32 s5, v232, 1
	s_waitcnt vmcnt(0)
	s_barrier
	s_and_saveexec_b64 s[6:7], s[4:5]
	s_cbranch_execz .LBB0_938
	s_add_i32 s3, 0, 0x20000
	v_mov_b32_e32 v0, s3
	s_waitcnt vmcnt(0) expcnt(0) lgkmcnt(0)
	buffer_inv sc1
	ds_read_b32 v2, v0
	s_add_i32 s3, 0, 0x20004
	v_mov_b32_e32 v0, s3
	ds_read_b32 v0, v0
	s_waitcnt lgkmcnt(1)
	v_cmp_ne_u32_e32 vcc, 0, v2
	s_cbranch_vccnz .LBB0_902
	s_add_u32 s8, s68, 0x23718200
	s_addc_u32 s9, s69, 0
	s_add_u32 s10, s68, 0x23718400
	s_addc_u32 s11, s69, 0
	s_add_u32 s12, s68, 0x23718500
	s_addc_u32 s13, s69, 0
	s_add_u32 s14, s68, 0x23718600
	s_addc_u32 s15, s69, 0
	s_add_u32 s16, s68, 0x23718700
	s_addc_u32 s17, s69, 0
	s_add_u32 s18, s68, 0x23718800
	s_addc_u32 s19, s69, 0
	s_add_u32 s20, s68, 0x23718900
	s_addc_u32 s21, s69, 0
	s_add_u32 s22, s68, 0x23718a00
	s_addc_u32 s23, s69, 0
	s_add_u32 s24, s68, 0x23718b00
	s_addc_u32 s25, s69, 0
	s_add_u32 s26, s68, 0x23718c00
	s_addc_u32 s27, s69, 0
	s_add_u32 s28, s68, 0x23718d00
	s_addc_u32 s29, s69, 0
	s_add_u32 s30, s68, 0x23718e00
	s_addc_u32 s31, s69, 0
	s_add_u32 s34, s68, 0x23718f00
	s_addc_u32 s35, s69, 0
	s_add_u32 s36, s68, 0x23719000
	s_load_dword s3, s[0:1], 0x110
	s_addc_u32 s37, s69, 0
	s_add_u32 s38, s68, 0x23719100
	s_addc_u32 s39, s69, 0
	s_add_u32 s40, s68, 0x23719200
	s_addc_u32 s41, s69, 0
	s_waitcnt lgkmcnt(0)
	s_mul_i32 s3, s65, s3
	s_add_u32 s42, s68, 0x23719300
	s_mul_i32 s3, s3, s64
	s_addc_u32 s43, s69, 0
	s_mov_b32 s50, 1
	v_mov_b32_e32 v16, 0
	s_branch .LBB0_890

.LBB0_959:
	s_cmp_lt_i32 s67, 12
	s_cbranch_scc1 .LBB0_1013
	s_waitcnt vmcnt(0)
	v_readlane_b32 s4, v232, 0
	v_readlane_b32 s5, v232, 1
	s_waitcnt vmcnt(0)
	s_barrier
	s_and_saveexec_b64 s[6:7], s[4:5]
	s_cbranch_execz .LBB0_1012
	s_add_i32 s3, 0, 0x20000
	v_mov_b32_e32 v0, s3
	s_waitcnt vmcnt(0) expcnt(0) lgkmcnt(0)
	buffer_inv sc1
	ds_read_b32 v2, v0
	s_add_i32 s3, 0, 0x20004
	v_mov_b32_e32 v0, s3
	ds_read_b32 v0, v0
	s_waitcnt lgkmcnt(1)
	v_cmp_ne_u32_e32 vcc, 0, v2
	s_cbranch_vccnz .LBB0_976
	s_add_u32 s8, s68, 0x23718200
	s_addc_u32 s9, s69, 0
	s_add_u32 s10, s68, 0x23718400
	s_addc_u32 s11, s69, 0
	s_add_u32 s12, s68, 0x23718500
	s_addc_u32 s13, s69, 0
	s_add_u32 s14, s68, 0x23718600
	s_addc_u32 s15, s69, 0
	s_add_u32 s16, s68, 0x23718700
	s_addc_u32 s17, s69, 0
	s_add_u32 s18, s68, 0x23718800
	s_addc_u32 s19, s69, 0
	s_add_u32 s20, s68, 0x23718900
	s_addc_u32 s21, s69, 0
	s_add_u32 s22, s68, 0x23718a00
	s_addc_u32 s23, s69, 0
	s_add_u32 s24, s68, 0x23718b00
	s_addc_u32 s25, s69, 0
	s_add_u32 s26, s68, 0x23718c00
	s_addc_u32 s27, s69, 0
	s_add_u32 s28, s68, 0x23718d00
	s_addc_u32 s29, s69, 0
	s_add_u32 s30, s68, 0x23718e00
	s_addc_u32 s31, s69, 0
	s_add_u32 s34, s68, 0x23718f00
	s_addc_u32 s35, s69, 0
	s_add_u32 s36, s68, 0x23719000
	s_load_dword s3, s[0:1], 0x110
	s_addc_u32 s37, s69, 0
	s_add_u32 s38, s68, 0x23719100
	s_addc_u32 s39, s69, 0
	s_add_u32 s40, s68, 0x23719200
	s_addc_u32 s41, s69, 0
	s_waitcnt lgkmcnt(0)
	s_mul_i32 s3, s65, s3
	s_add_u32 s42, s68, 0x23719300
	s_mul_i32 s3, s3, s64
	s_addc_u32 s43, s69, 0
	s_mov_b32 s50, 1
	v_mov_b32_e32 v16, 0
	s_branch .LBB0_964

.LBB0_1019:
	s_or_b64 exec, exec, s[6:7]
	s_cmp_lt_i32 s67, 13
	s_cbranch_scc1 .LBB0_1073
	s_waitcnt vmcnt(0)
	v_readlane_b32 s4, v232, 0
	v_readlane_b32 s5, v232, 1
	s_waitcnt vmcnt(0)
	s_barrier
	s_and_saveexec_b64 s[6:7], s[4:5]
	s_cbranch_execz .LBB0_1072
	s_add_i32 s4, 0, 0x20000
	v_mov_b32_e32 v0, s4
	s_waitcnt vmcnt(0) expcnt(0) lgkmcnt(0)
	buffer_inv sc1
	ds_read_b32 v2, v0
	s_add_i32 s4, 0, 0x20004
	v_mov_b32_e32 v0, s4
	ds_read_b32 v0, v0
	s_waitcnt lgkmcnt(1)
	v_cmp_ne_u32_e32 vcc, 0, v2
	s_cbranch_vccnz .LBB0_1036
	s_add_u32 s8, s68, 0x23718200
	s_addc_u32 s9, s69, 0
	s_add_u32 s10, s68, 0x23718400
	s_addc_u32 s11, s69, 0
	s_add_u32 s12, s68, 0x23718500
	s_addc_u32 s13, s69, 0
	s_add_u32 s14, s68, 0x23718600
	s_addc_u32 s15, s69, 0
	s_add_u32 s16, s68, 0x23718700
	s_addc_u32 s17, s69, 0
	s_add_u32 s18, s68, 0x23718800
	s_addc_u32 s19, s69, 0
	s_add_u32 s20, s68, 0x23718900
	s_addc_u32 s21, s69, 0
	s_add_u32 s22, s68, 0x23718a00
	s_addc_u32 s23, s69, 0
	s_add_u32 s24, s68, 0x23718b00
	s_addc_u32 s25, s69, 0
	s_add_u32 s26, s68, 0x23718c00
	s_addc_u32 s27, s69, 0
	s_add_u32 s28, s68, 0x23718d00
	s_addc_u32 s29, s69, 0
	s_add_u32 s30, s68, 0x23718e00
	s_addc_u32 s31, s69, 0
	s_add_u32 s34, s68, 0x23718f00
	s_addc_u32 s35, s69, 0
	s_add_u32 s36, s68, 0x23719000
	s_load_dword s4, s[0:1], 0x110
	s_addc_u32 s37, s69, 0
	s_add_u32 s38, s68, 0x23719100
	s_addc_u32 s39, s69, 0
	s_add_u32 s40, s68, 0x23719200
	s_addc_u32 s41, s69, 0
	s_waitcnt lgkmcnt(0)
	s_mul_i32 s4, s65, s4
	s_add_u32 s42, s68, 0x23719300
	s_mul_i32 s3, s4, s3
	s_addc_u32 s43, s69, 0
	s_mov_b32 s50, 1
	v_mov_b32_e32 v16, 0
	s_branch .LBB0_1024

.LBB0_1094:
	s_cmp_lt_i32 s67, 14
	s_cbranch_scc1 .LBB0_1148
	s_waitcnt vmcnt(0)
	v_readlane_b32 s4, v232, 0
	v_readlane_b32 s5, v232, 1
	s_waitcnt vmcnt(0)
	s_barrier
	s_and_saveexec_b64 s[6:7], s[4:5]
	s_cbranch_execz .LBB0_1147
	s_add_i32 s4, 0, 0x20000
	v_mov_b32_e32 v0, s4
	s_waitcnt vmcnt(0) expcnt(0) lgkmcnt(0)
	buffer_inv sc1
	ds_read_b32 v2, v0
	s_add_i32 s4, 0, 0x20004
	v_mov_b32_e32 v0, s4
	ds_read_b32 v0, v0
	s_waitcnt lgkmcnt(1)
	v_cmp_ne_u32_e32 vcc, 0, v2
	s_cbranch_vccnz .LBB0_1111
	s_add_u32 s8, s68, 0x23718200
	s_addc_u32 s9, s69, 0
	s_add_u32 s10, s68, 0x23718400
	s_addc_u32 s11, s69, 0
	s_add_u32 s12, s68, 0x23718500
	s_addc_u32 s13, s69, 0
	s_add_u32 s14, s68, 0x23718600
	s_addc_u32 s15, s69, 0
	s_add_u32 s16, s68, 0x23718700
	s_addc_u32 s17, s69, 0
	s_add_u32 s18, s68, 0x23718800
	s_addc_u32 s19, s69, 0
	s_add_u32 s20, s68, 0x23718900
	s_addc_u32 s21, s69, 0
	s_add_u32 s22, s68, 0x23718a00
	s_addc_u32 s23, s69, 0
	s_add_u32 s24, s68, 0x23718b00
	s_addc_u32 s25, s69, 0
	s_add_u32 s26, s68, 0x23718c00
	s_addc_u32 s27, s69, 0
	s_add_u32 s28, s68, 0x23718d00
	s_addc_u32 s29, s69, 0
	s_add_u32 s30, s68, 0x23718e00
	s_addc_u32 s31, s69, 0
	s_add_u32 s34, s68, 0x23718f00
	s_addc_u32 s35, s69, 0
	s_add_u32 s36, s68, 0x23719000
	s_load_dword s4, s[0:1], 0x110
	s_addc_u32 s37, s69, 0
	s_add_u32 s38, s68, 0x23719100
	s_addc_u32 s39, s69, 0
	s_add_u32 s40, s68, 0x23719200
	s_addc_u32 s41, s69, 0
	s_waitcnt lgkmcnt(0)
	s_mul_i32 s4, s65, s4
	s_add_u32 s42, s68, 0x23719300
	s_mul_i32 s3, s4, s3
	s_addc_u32 s43, s69, 0
	s_mov_b32 s50, 1
	v_mov_b32_e32 v16, 0
	s_branch .LBB0_1099

.LBB0_1172:
	s_cmp_lt_i32 s67, 15
	s_cbranch_scc1 .LBB0_1226
	s_waitcnt vmcnt(0)
	v_readlane_b32 s4, v232, 0
	v_readlane_b32 s5, v232, 1
	s_waitcnt vmcnt(0)
	s_barrier
	s_and_saveexec_b64 s[6:7], s[4:5]
	s_cbranch_execz .LBB0_1225
	s_add_i32 s3, 0, 0x20000
	v_mov_b32_e32 v0, s3
	s_waitcnt vmcnt(0) expcnt(0) lgkmcnt(0)
	buffer_inv sc1
	ds_read_b32 v2, v0
	s_add_i32 s3, 0, 0x20004
	v_mov_b32_e32 v0, s3
	ds_read_b32 v0, v0
	s_waitcnt lgkmcnt(1)
	v_cmp_ne_u32_e32 vcc, 0, v2
	s_cbranch_vccnz .LBB0_1189
	s_add_u32 s8, s68, 0x23718200
	s_addc_u32 s9, s69, 0
	s_add_u32 s10, s68, 0x23718400
	s_addc_u32 s11, s69, 0
	s_add_u32 s12, s68, 0x23718500
	s_addc_u32 s13, s69, 0
	s_add_u32 s14, s68, 0x23718600
	s_addc_u32 s15, s69, 0
	s_add_u32 s16, s68, 0x23718700
	s_addc_u32 s17, s69, 0
	s_add_u32 s18, s68, 0x23718800
	s_addc_u32 s19, s69, 0
	s_add_u32 s20, s68, 0x23718900
	s_addc_u32 s21, s69, 0
	s_add_u32 s22, s68, 0x23718a00
	s_addc_u32 s23, s69, 0
	s_add_u32 s24, s68, 0x23718b00
	s_addc_u32 s25, s69, 0
	s_add_u32 s26, s68, 0x23718c00
	s_addc_u32 s27, s69, 0
	s_add_u32 s28, s68, 0x23718d00
	s_addc_u32 s29, s69, 0
	s_add_u32 s30, s68, 0x23718e00
	s_addc_u32 s31, s69, 0
	s_add_u32 s34, s68, 0x23718f00
	s_addc_u32 s35, s69, 0
	s_add_u32 s36, s68, 0x23719000
	s_load_dword s3, s[0:1], 0x110
	s_addc_u32 s37, s69, 0
	s_add_u32 s38, s68, 0x23719100
	s_addc_u32 s39, s69, 0
	s_add_u32 s40, s68, 0x23719200
	s_addc_u32 s41, s69, 0
	s_waitcnt lgkmcnt(0)
	s_mul_i32 s3, s65, s3
	s_add_u32 s42, s68, 0x23719300
	s_mul_i32 s3, s3, s64
	s_addc_u32 s43, s69, 0
	s_mov_b32 s50, 1
	v_mov_b32_e32 v16, 0
	s_branch .LBB0_1177

.LBB0_1232:
	s_or_b64 exec, exec, s[6:7]
	s_cmp_lt_i32 s67, 16
	s_cbranch_scc1 .LBB0_1286
	s_waitcnt vmcnt(0)
	v_readlane_b32 s4, v232, 0
	v_readlane_b32 s5, v232, 1
	s_waitcnt vmcnt(0)
	s_barrier
	s_and_saveexec_b64 s[6:7], s[4:5]
	s_cbranch_execz .LBB0_1285
	s_add_i32 s4, 0, 0x20000
	v_mov_b32_e32 v0, s4
	s_waitcnt vmcnt(0) expcnt(0) lgkmcnt(0)
	buffer_inv sc1
	ds_read_b32 v2, v0
	s_add_i32 s4, 0, 0x20004
	v_mov_b32_e32 v0, s4
	ds_read_b32 v0, v0
	s_waitcnt lgkmcnt(1)
	v_cmp_ne_u32_e32 vcc, 0, v2
	s_cbranch_vccnz .LBB0_1249
	s_add_u32 s8, s68, 0x23718200
	s_addc_u32 s9, s69, 0
	s_add_u32 s10, s68, 0x23718400
	s_addc_u32 s11, s69, 0
	s_add_u32 s12, s68, 0x23718500
	s_addc_u32 s13, s69, 0
	s_add_u32 s14, s68, 0x23718600
	s_addc_u32 s15, s69, 0
	s_add_u32 s16, s68, 0x23718700
	s_addc_u32 s17, s69, 0
	s_add_u32 s18, s68, 0x23718800
	s_addc_u32 s19, s69, 0
	s_add_u32 s20, s68, 0x23718900
	s_addc_u32 s21, s69, 0
	s_add_u32 s22, s68, 0x23718a00
	s_addc_u32 s23, s69, 0
	s_add_u32 s24, s68, 0x23718b00
	s_addc_u32 s25, s69, 0
	s_add_u32 s26, s68, 0x23718c00
	s_addc_u32 s27, s69, 0
	s_add_u32 s28, s68, 0x23718d00
	s_addc_u32 s29, s69, 0
	s_add_u32 s30, s68, 0x23718e00
	s_addc_u32 s31, s69, 0
	s_add_u32 s34, s68, 0x23718f00
	s_addc_u32 s35, s69, 0
	s_add_u32 s36, s68, 0x23719000
	s_load_dword s4, s[0:1], 0x110
	s_addc_u32 s37, s69, 0
	s_add_u32 s38, s68, 0x23719100
	s_addc_u32 s39, s69, 0
	s_add_u32 s40, s68, 0x23719200
	s_addc_u32 s41, s69, 0
	s_waitcnt lgkmcnt(0)
	s_mul_i32 s4, s65, s4
	s_add_u32 s42, s68, 0x23719300
	s_mul_i32 s3, s4, s3
	s_addc_u32 s43, s69, 0
	s_mov_b32 s50, 1
	v_mov_b32_e32 v16, 0
	s_branch .LBB0_1237

.LBB0_1307:
	s_cmp_lt_i32 s67, 17
	s_cbranch_scc1 .LBB0_1361
	s_waitcnt vmcnt(0)
	v_readlane_b32 s4, v232, 0
	v_readlane_b32 s5, v232, 1
	s_waitcnt vmcnt(0)
	s_barrier
	s_and_saveexec_b64 s[6:7], s[4:5]
	s_cbranch_execz .LBB0_1360
	s_add_i32 s4, 0, 0x20000
	v_mov_b32_e32 v0, s4
	s_waitcnt vmcnt(0) expcnt(0) lgkmcnt(0)
	buffer_inv sc1
	ds_read_b32 v2, v0
	s_add_i32 s4, 0, 0x20004
	v_mov_b32_e32 v0, s4
	ds_read_b32 v0, v0
	s_waitcnt lgkmcnt(1)
	v_cmp_ne_u32_e32 vcc, 0, v2
	s_cbranch_vccnz .LBB0_1324
	s_add_u32 s8, s68, 0x23718200
	s_addc_u32 s9, s69, 0
	s_add_u32 s10, s68, 0x23718400
	s_addc_u32 s11, s69, 0
	s_add_u32 s12, s68, 0x23718500
	s_addc_u32 s13, s69, 0
	s_add_u32 s14, s68, 0x23718600
	s_addc_u32 s15, s69, 0
	s_add_u32 s16, s68, 0x23718700
	s_addc_u32 s17, s69, 0
	s_add_u32 s18, s68, 0x23718800
	s_addc_u32 s19, s69, 0
	s_add_u32 s20, s68, 0x23718900
	s_addc_u32 s21, s69, 0
	s_add_u32 s22, s68, 0x23718a00
	s_addc_u32 s23, s69, 0
	s_add_u32 s24, s68, 0x23718b00
	s_addc_u32 s25, s69, 0
	s_add_u32 s26, s68, 0x23718c00
	s_addc_u32 s27, s69, 0
	s_add_u32 s28, s68, 0x23718d00
	s_addc_u32 s29, s69, 0
	s_add_u32 s30, s68, 0x23718e00
	s_addc_u32 s31, s69, 0
	s_add_u32 s34, s68, 0x23718f00
	s_addc_u32 s35, s69, 0
	s_add_u32 s36, s68, 0x23719000
	s_load_dword s4, s[0:1], 0x110
	s_addc_u32 s37, s69, 0
	s_add_u32 s38, s68, 0x23719100
	s_addc_u32 s39, s69, 0
	s_add_u32 s40, s68, 0x23719200
	s_addc_u32 s41, s69, 0
	s_waitcnt lgkmcnt(0)
	s_mul_i32 s4, s65, s4
	s_add_u32 s42, s68, 0x23719300
	s_mul_i32 s3, s4, s3
	s_addc_u32 s43, s69, 0
	s_mov_b32 s50, 1
	v_mov_b32_e32 v16, 0
	s_branch .LBB0_1312

.LBB0_1385:
	s_cmp_lt_i32 s67, 18
	s_cbranch_scc1 .LBB0_1439
	s_waitcnt vmcnt(0)
	v_readlane_b32 s4, v232, 0
	v_readlane_b32 s5, v232, 1
	s_waitcnt vmcnt(0)
	s_barrier
	s_and_saveexec_b64 s[6:7], s[4:5]
	s_cbranch_execz .LBB0_1438
	s_add_i32 s3, 0, 0x20000
	v_mov_b32_e32 v0, s3
	s_waitcnt vmcnt(0) expcnt(0) lgkmcnt(0)
	buffer_inv sc1
	ds_read_b32 v2, v0
	s_add_i32 s3, 0, 0x20004
	v_mov_b32_e32 v0, s3
	ds_read_b32 v0, v0
	s_waitcnt lgkmcnt(1)
	v_cmp_ne_u32_e32 vcc, 0, v2
	s_cbranch_vccnz .LBB0_1402
	s_add_u32 s8, s68, 0x23718200
	s_addc_u32 s9, s69, 0
	s_add_u32 s10, s68, 0x23718400
	s_addc_u32 s11, s69, 0
	s_add_u32 s12, s68, 0x23718500
	s_addc_u32 s13, s69, 0
	s_add_u32 s14, s68, 0x23718600
	s_addc_u32 s15, s69, 0
	s_add_u32 s16, s68, 0x23718700
	s_addc_u32 s17, s69, 0
	s_add_u32 s18, s68, 0x23718800
	s_addc_u32 s19, s69, 0
	s_add_u32 s20, s68, 0x23718900
	s_addc_u32 s21, s69, 0
	s_add_u32 s22, s68, 0x23718a00
	s_addc_u32 s23, s69, 0
	s_add_u32 s24, s68, 0x23718b00
	s_addc_u32 s25, s69, 0
	s_add_u32 s26, s68, 0x23718c00
	s_addc_u32 s27, s69, 0
	s_add_u32 s28, s68, 0x23718d00
	s_addc_u32 s29, s69, 0
	s_add_u32 s30, s68, 0x23718e00
	s_addc_u32 s31, s69, 0
	s_add_u32 s34, s68, 0x23718f00
	s_addc_u32 s35, s69, 0
	s_add_u32 s36, s68, 0x23719000
	s_load_dword s3, s[0:1], 0x110
	s_addc_u32 s37, s69, 0
	s_add_u32 s38, s68, 0x23719100
	s_addc_u32 s39, s69, 0
	s_add_u32 s40, s68, 0x23719200
	s_addc_u32 s41, s69, 0
	s_waitcnt lgkmcnt(0)
	s_mul_i32 s3, s65, s3
	s_add_u32 s42, s68, 0x23719300
	s_mul_i32 s3, s3, s64
	s_addc_u32 s43, s69, 0
	s_mov_b32 s50, 1
	v_mov_b32_e32 v16, 0
	s_branch .LBB0_1390

.LBB0_1445:
	s_or_b64 exec, exec, s[6:7]
	s_cmp_lt_i32 s67, 19
	s_cbranch_scc1 .LBB0_1499
	s_waitcnt vmcnt(0)
	v_readlane_b32 s4, v232, 0
	v_readlane_b32 s5, v232, 1
	s_waitcnt vmcnt(0)
	s_barrier
	s_and_saveexec_b64 s[6:7], s[4:5]
	s_cbranch_execz .LBB0_1498
	s_add_i32 s4, 0, 0x20000
	v_mov_b32_e32 v0, s4
	s_waitcnt vmcnt(0) expcnt(0) lgkmcnt(0)
	buffer_inv sc1
	ds_read_b32 v2, v0
	s_add_i32 s4, 0, 0x20004
	v_mov_b32_e32 v0, s4
	ds_read_b32 v0, v0
	s_waitcnt lgkmcnt(1)
	v_cmp_ne_u32_e32 vcc, 0, v2
	s_cbranch_vccnz .LBB0_1462
	s_add_u32 s8, s68, 0x23718200
	s_addc_u32 s9, s69, 0
	s_add_u32 s10, s68, 0x23718400
	s_addc_u32 s11, s69, 0
	s_add_u32 s12, s68, 0x23718500
	s_addc_u32 s13, s69, 0
	s_add_u32 s14, s68, 0x23718600
	s_addc_u32 s15, s69, 0
	s_add_u32 s16, s68, 0x23718700
	s_addc_u32 s17, s69, 0
	s_add_u32 s18, s68, 0x23718800
	s_addc_u32 s19, s69, 0
	s_add_u32 s20, s68, 0x23718900
	s_addc_u32 s21, s69, 0
	s_add_u32 s22, s68, 0x23718a00
	s_addc_u32 s23, s69, 0
	s_add_u32 s24, s68, 0x23718b00
	s_addc_u32 s25, s69, 0
	s_add_u32 s26, s68, 0x23718c00
	s_addc_u32 s27, s69, 0
	s_add_u32 s28, s68, 0x23718d00
	s_addc_u32 s29, s69, 0
	s_add_u32 s30, s68, 0x23718e00
	s_addc_u32 s31, s69, 0
	s_add_u32 s34, s68, 0x23718f00
	s_addc_u32 s35, s69, 0
	s_add_u32 s36, s68, 0x23719000
	s_load_dword s4, s[0:1], 0x110
	s_addc_u32 s37, s69, 0
	s_add_u32 s38, s68, 0x23719100
	s_addc_u32 s39, s69, 0
	s_add_u32 s40, s68, 0x23719200
	s_addc_u32 s41, s69, 0
	s_waitcnt lgkmcnt(0)
	s_mul_i32 s4, s65, s4
	s_add_u32 s42, s68, 0x23719300
	s_mul_i32 s3, s4, s3
	s_addc_u32 s43, s69, 0
	s_mov_b32 s50, 1
	v_mov_b32_e32 v16, 0
	s_branch .LBB0_1450

.LBB0_1512:
	s_or_b64 exec, exec, s[78:79]
	s_cmp_lt_u32 s67, 20
	s_cbranch_scc1 .LBB0_1566
	s_waitcnt vmcnt(0)
	v_readlane_b32 s4, v232, 0
	v_readlane_b32 s5, v232, 1
	s_waitcnt vmcnt(0)
	s_barrier
	s_and_saveexec_b64 s[6:7], s[4:5]
	s_cbranch_execz .LBB0_1565
	s_add_i32 s3, 0, 0x20000
	v_mov_b32_e32 v0, s3
	s_waitcnt vmcnt(0) expcnt(0) lgkmcnt(0)
	buffer_inv sc1
	ds_read_b32 v2, v0
	s_add_i32 s3, 0, 0x20004
	v_mov_b32_e32 v0, s3
	ds_read_b32 v0, v0
	s_waitcnt lgkmcnt(1)
	v_cmp_ne_u32_e32 vcc, 0, v2
	s_cbranch_vccnz .LBB0_1529
	s_add_u32 s8, s68, 0x23718200
	s_addc_u32 s9, s69, 0
	s_add_u32 s10, s68, 0x23718400
	s_addc_u32 s11, s69, 0
	s_add_u32 s12, s68, 0x23718500
	s_addc_u32 s13, s69, 0
	s_add_u32 s14, s68, 0x23718600
	s_addc_u32 s15, s69, 0
	s_add_u32 s16, s68, 0x23718700
	s_addc_u32 s17, s69, 0
	s_add_u32 s18, s68, 0x23718800
	s_addc_u32 s19, s69, 0
	s_add_u32 s20, s68, 0x23718900
	s_addc_u32 s21, s69, 0
	s_add_u32 s22, s68, 0x23718a00
	s_addc_u32 s23, s69, 0
	s_add_u32 s24, s68, 0x23718b00
	s_addc_u32 s25, s69, 0
	s_add_u32 s26, s68, 0x23718c00
	s_addc_u32 s27, s69, 0
	s_add_u32 s28, s68, 0x23718d00
	s_addc_u32 s29, s69, 0
	s_add_u32 s30, s68, 0x23718e00
	s_addc_u32 s31, s69, 0
	s_add_u32 s34, s68, 0x23718f00
	s_addc_u32 s35, s69, 0
	s_add_u32 s36, s68, 0x23719000
	s_load_dword s3, s[0:1], 0x110
	s_addc_u32 s37, s69, 0
	s_add_u32 s38, s68, 0x23719100
	s_addc_u32 s39, s69, 0
	s_add_u32 s40, s68, 0x23719200
	s_addc_u32 s41, s69, 0
	s_waitcnt lgkmcnt(0)
	s_mul_i32 s3, s65, s3
	s_add_u32 s42, s68, 0x23719300
	s_mul_i32 s3, s3, s64
	s_addc_u32 s43, s69, 0
	s_mov_b32 s50, 1
	v_mov_b32_e32 v16, 0
	s_branch .LBB0_1517

.LBB0_1634:
	s_cmp_gt_i32 s67, 20
	s_cbranch_scc0 .LBB0_1688
	s_waitcnt vmcnt(0)
	v_readlane_b32 s4, v232, 0
	v_readlane_b32 s5, v232, 1
	s_waitcnt vmcnt(0)
	s_barrier
	s_and_saveexec_b64 s[6:7], s[4:5]
	s_cbranch_execz .LBB0_1687
	s_add_i32 s4, 0, 0x20000
	v_mov_b32_e32 v0, s4
	s_waitcnt vmcnt(0) expcnt(0) lgkmcnt(0)
	buffer_inv sc1
	ds_read_b32 v2, v0
	s_add_i32 s4, 0, 0x20004
	v_mov_b32_e32 v0, s4
	ds_read_b32 v0, v0
	s_waitcnt lgkmcnt(1)
	v_cmp_ne_u32_e32 vcc, 0, v2
	s_cbranch_vccnz .LBB0_1651
	s_add_u32 s8, s68, 0x23718200
	s_addc_u32 s9, s69, 0
	s_add_u32 s10, s68, 0x23718400
	s_addc_u32 s11, s69, 0
	s_add_u32 s12, s68, 0x23718500
	s_addc_u32 s13, s69, 0
	s_add_u32 s14, s68, 0x23718600
	s_addc_u32 s15, s69, 0
	s_add_u32 s16, s68, 0x23718700
	s_addc_u32 s17, s69, 0
	s_add_u32 s18, s68, 0x23718800
	s_addc_u32 s19, s69, 0
	s_add_u32 s20, s68, 0x23718900
	s_addc_u32 s21, s69, 0
	s_add_u32 s22, s68, 0x23718a00
	s_addc_u32 s23, s69, 0
	s_add_u32 s24, s68, 0x23718b00
	s_addc_u32 s25, s69, 0
	s_add_u32 s26, s68, 0x23718c00
	s_addc_u32 s27, s69, 0
	s_add_u32 s28, s68, 0x23718d00
	s_addc_u32 s29, s69, 0
	s_add_u32 s30, s68, 0x23718e00
	s_addc_u32 s31, s69, 0
	s_add_u32 s34, s68, 0x23718f00
	s_addc_u32 s35, s69, 0
	s_add_u32 s36, s68, 0x23719000
	s_load_dword s4, s[0:1], 0x110
	s_addc_u32 s37, s69, 0
	s_add_u32 s38, s68, 0x23719100
	s_addc_u32 s39, s69, 0
	s_add_u32 s40, s68, 0x23719200
	s_addc_u32 s41, s69, 0
	s_waitcnt lgkmcnt(0)
	s_mul_i32 s4, s65, s4
	s_add_u32 s42, s68, 0x23719300
	s_mul_i32 s3, s4, s3
	s_addc_u32 s43, s69, 0
	s_mov_b32 s50, 1
	v_mov_b32_e32 v16, 0
	s_branch .LBB0_1639

.LBB0_1694:
	s_or_b64 exec, exec, s[6:7]
	s_cmp_lt_i32 s67, 22
	s_cbranch_scc1 .LBB0_1748
	s_waitcnt vmcnt(0)
	v_readlane_b32 s4, v232, 0
	v_readlane_b32 s5, v232, 1
	s_waitcnt vmcnt(0)
	s_barrier
	s_and_saveexec_b64 s[6:7], s[4:5]
	s_cbranch_execz .LBB0_1747
	s_add_i32 s4, 0, 0x20000
	v_mov_b32_e32 v0, s4
	s_waitcnt vmcnt(0) expcnt(0) lgkmcnt(0)
	buffer_inv sc1
	ds_read_b32 v2, v0
	s_add_i32 s4, 0, 0x20004
	v_mov_b32_e32 v0, s4
	ds_read_b32 v0, v0
	s_waitcnt lgkmcnt(1)
	v_cmp_ne_u32_e32 vcc, 0, v2
	s_cbranch_vccnz .LBB0_1711
	s_add_u32 s8, s68, 0x23718200
	s_addc_u32 s9, s69, 0
	s_add_u32 s10, s68, 0x23718400
	s_addc_u32 s11, s69, 0
	s_add_u32 s12, s68, 0x23718500
	s_addc_u32 s13, s69, 0
	s_add_u32 s14, s68, 0x23718600
	s_addc_u32 s15, s69, 0
	s_add_u32 s16, s68, 0x23718700
	s_addc_u32 s17, s69, 0
	s_add_u32 s18, s68, 0x23718800
	s_addc_u32 s19, s69, 0
	s_add_u32 s20, s68, 0x23718900
	s_addc_u32 s21, s69, 0
	s_add_u32 s22, s68, 0x23718a00
	s_addc_u32 s23, s69, 0
	s_add_u32 s24, s68, 0x23718b00
	s_addc_u32 s25, s69, 0
	s_add_u32 s26, s68, 0x23718c00
	s_addc_u32 s27, s69, 0
	s_add_u32 s28, s68, 0x23718d00
	s_addc_u32 s29, s69, 0
	s_add_u32 s30, s68, 0x23718e00
	s_addc_u32 s31, s69, 0
	s_add_u32 s34, s68, 0x23718f00
	s_addc_u32 s35, s69, 0
	s_add_u32 s36, s68, 0x23719000
	s_load_dword s4, s[0:1], 0x110
	s_addc_u32 s37, s69, 0
	s_add_u32 s38, s68, 0x23719100
	s_addc_u32 s39, s69, 0
	s_add_u32 s40, s68, 0x23719200
	s_addc_u32 s41, s69, 0
	s_waitcnt lgkmcnt(0)
	s_mul_i32 s4, s65, s4
	s_add_u32 s42, s68, 0x23719300
	s_mul_i32 s3, s4, s3
	s_addc_u32 s43, s69, 0
	s_mov_b32 s50, 1
	v_mov_b32_e32 v16, 0
	s_branch .LBB0_1699

.LBB0_1769:
	s_cmp_lt_i32 s67, 23
	s_cbranch_scc1 .LBB0_1823
	s_waitcnt vmcnt(0)
	v_readlane_b32 s4, v232, 0
	v_readlane_b32 s5, v232, 1
	s_waitcnt vmcnt(0)
	s_barrier
	s_and_saveexec_b64 s[6:7], s[4:5]
	s_cbranch_execz .LBB0_1822
	s_add_i32 s4, 0, 0x20000
	v_mov_b32_e32 v0, s4
	s_waitcnt vmcnt(0) expcnt(0) lgkmcnt(0)
	buffer_inv sc1
	ds_read_b32 v2, v0
	s_add_i32 s4, 0, 0x20004
	v_mov_b32_e32 v0, s4
	ds_read_b32 v0, v0
	s_waitcnt lgkmcnt(1)
	v_cmp_ne_u32_e32 vcc, 0, v2
	s_cbranch_vccnz .LBB0_1786
	s_add_u32 s8, s68, 0x23718200
	s_addc_u32 s9, s69, 0
	s_add_u32 s10, s68, 0x23718400
	s_addc_u32 s11, s69, 0
	s_add_u32 s12, s68, 0x23718500
	s_addc_u32 s13, s69, 0
	s_add_u32 s14, s68, 0x23718600
	s_addc_u32 s15, s69, 0
	s_add_u32 s16, s68, 0x23718700
	s_addc_u32 s17, s69, 0
	s_add_u32 s18, s68, 0x23718800
	s_addc_u32 s19, s69, 0
	s_add_u32 s20, s68, 0x23718900
	s_addc_u32 s21, s69, 0
	s_add_u32 s22, s68, 0x23718a00
	s_addc_u32 s23, s69, 0
	s_add_u32 s24, s68, 0x23718b00
	s_addc_u32 s25, s69, 0
	s_add_u32 s26, s68, 0x23718c00
	s_addc_u32 s27, s69, 0
	s_add_u32 s28, s68, 0x23718d00
	s_addc_u32 s29, s69, 0
	s_add_u32 s30, s68, 0x23718e00
	s_addc_u32 s31, s69, 0
	s_add_u32 s34, s68, 0x23718f00
	s_addc_u32 s35, s69, 0
	s_add_u32 s36, s68, 0x23719000
	s_load_dword s4, s[0:1], 0x110
	s_addc_u32 s37, s69, 0
	s_add_u32 s38, s68, 0x23719100
	s_addc_u32 s39, s69, 0
	s_add_u32 s40, s68, 0x23719200
	s_addc_u32 s41, s69, 0
	s_waitcnt lgkmcnt(0)
	s_mul_i32 s4, s65, s4
	s_add_u32 s42, s68, 0x23719300
	s_mul_i32 s3, s4, s3
	s_addc_u32 s43, s69, 0
	s_mov_b32 s50, 1
	v_mov_b32_e32 v16, 0
	s_branch .LBB0_1774

.LBB0_1847:
	s_cmp_lt_i32 s67, 24
	s_cbranch_scc1 .LBB0_1901
	s_waitcnt vmcnt(0)
	v_readlane_b32 s4, v232, 0
	v_readlane_b32 s5, v232, 1
	s_waitcnt vmcnt(0)
	s_barrier
	s_and_saveexec_b64 s[6:7], s[4:5]
	s_cbranch_execz .LBB0_1900
	s_add_i32 s3, 0, 0x20000
	v_mov_b32_e32 v0, s3
	s_waitcnt vmcnt(0) expcnt(0) lgkmcnt(0)
	buffer_inv sc1
	ds_read_b32 v2, v0
	s_add_i32 s3, 0, 0x20004
	v_mov_b32_e32 v0, s3
	ds_read_b32 v0, v0
	s_waitcnt lgkmcnt(1)
	v_cmp_ne_u32_e32 vcc, 0, v2
	s_cbranch_vccnz .LBB0_1864
	s_add_u32 s8, s68, 0x23718200
	s_addc_u32 s9, s69, 0
	s_add_u32 s10, s68, 0x23718400
	s_addc_u32 s11, s69, 0
	s_add_u32 s12, s68, 0x23718500
	s_addc_u32 s13, s69, 0
	s_add_u32 s14, s68, 0x23718600
	s_addc_u32 s15, s69, 0
	s_add_u32 s16, s68, 0x23718700
	s_addc_u32 s17, s69, 0
	s_add_u32 s18, s68, 0x23718800
	s_addc_u32 s19, s69, 0
	s_add_u32 s20, s68, 0x23718900
	s_addc_u32 s21, s69, 0
	s_add_u32 s22, s68, 0x23718a00
	s_addc_u32 s23, s69, 0
	s_add_u32 s24, s68, 0x23718b00
	s_addc_u32 s25, s69, 0
	s_add_u32 s26, s68, 0x23718c00
	s_addc_u32 s27, s69, 0
	s_add_u32 s28, s68, 0x23718d00
	s_addc_u32 s29, s69, 0
	s_add_u32 s30, s68, 0x23718e00
	s_addc_u32 s31, s69, 0
	s_add_u32 s34, s68, 0x23718f00
	s_addc_u32 s35, s69, 0
	s_add_u32 s36, s68, 0x23719000
	s_load_dword s3, s[0:1], 0x110
	s_addc_u32 s37, s69, 0
	s_add_u32 s38, s68, 0x23719100
	s_addc_u32 s39, s69, 0
	s_add_u32 s40, s68, 0x23719200
	s_addc_u32 s41, s69, 0
	s_waitcnt lgkmcnt(0)
	s_mul_i32 s3, s65, s3
	s_add_u32 s42, s68, 0x23719300
	s_mul_i32 s3, s3, s64
	s_addc_u32 s43, s69, 0
	s_mov_b32 s50, 1
	v_mov_b32_e32 v16, 0
	s_branch .LBB0_1852

.LBB0_1907:
	s_or_b64 exec, exec, s[6:7]
	s_cmp_lt_i32 s67, 25
	s_cbranch_scc1 .LBB0_1961
	s_waitcnt vmcnt(0)
	v_readlane_b32 s4, v232, 0
	v_readlane_b32 s5, v232, 1
	s_waitcnt vmcnt(0)
	s_barrier
	s_and_saveexec_b64 s[6:7], s[4:5]
	s_cbranch_execz .LBB0_1960
	s_add_i32 s4, 0, 0x20000
	v_mov_b32_e32 v0, s4
	s_waitcnt vmcnt(0) expcnt(0) lgkmcnt(0)
	buffer_inv sc1
	ds_read_b32 v2, v0
	s_add_i32 s4, 0, 0x20004
	v_mov_b32_e32 v0, s4
	ds_read_b32 v0, v0
	s_waitcnt lgkmcnt(1)
	v_cmp_ne_u32_e32 vcc, 0, v2
	s_cbranch_vccnz .LBB0_1924
	s_add_u32 s8, s68, 0x23718200
	s_addc_u32 s9, s69, 0
	s_add_u32 s10, s68, 0x23718400
	s_addc_u32 s11, s69, 0
	s_add_u32 s12, s68, 0x23718500
	s_addc_u32 s13, s69, 0
	s_add_u32 s14, s68, 0x23718600
	s_addc_u32 s15, s69, 0
	s_add_u32 s16, s68, 0x23718700
	s_addc_u32 s17, s69, 0
	s_add_u32 s18, s68, 0x23718800
	s_addc_u32 s19, s69, 0
	s_add_u32 s20, s68, 0x23718900
	s_addc_u32 s21, s69, 0
	s_add_u32 s22, s68, 0x23718a00
	s_addc_u32 s23, s69, 0
	s_add_u32 s24, s68, 0x23718b00
	s_addc_u32 s25, s69, 0
	s_add_u32 s26, s68, 0x23718c00
	s_addc_u32 s27, s69, 0
	s_add_u32 s28, s68, 0x23718d00
	s_addc_u32 s29, s69, 0
	s_add_u32 s30, s68, 0x23718e00
	s_addc_u32 s31, s69, 0
	s_add_u32 s34, s68, 0x23718f00
	s_addc_u32 s35, s69, 0
	s_add_u32 s36, s68, 0x23719000
	s_load_dword s4, s[0:1], 0x110
	s_addc_u32 s37, s69, 0
	s_add_u32 s38, s68, 0x23719100
	s_addc_u32 s39, s69, 0
	s_add_u32 s40, s68, 0x23719200
	s_addc_u32 s41, s69, 0
	s_waitcnt lgkmcnt(0)
	s_mul_i32 s4, s65, s4
	s_add_u32 s42, s68, 0x23719300
	s_mul_i32 s3, s4, s3
	s_addc_u32 s43, s69, 0
	s_mov_b32 s50, 1
	v_mov_b32_e32 v16, 0
	s_branch .LBB0_1912

.LBB0_1982:
	s_cmp_lt_i32 s67, 26
	s_cbranch_scc1 .LBB0_2036
	s_waitcnt vmcnt(0)
	v_readlane_b32 s4, v232, 0
	v_readlane_b32 s5, v232, 1
	s_waitcnt vmcnt(0)
	s_barrier
	s_and_saveexec_b64 s[6:7], s[4:5]
	s_cbranch_execz .LBB0_2035
	s_add_i32 s4, 0, 0x20000
	v_mov_b32_e32 v0, s4
	s_waitcnt vmcnt(0) expcnt(0) lgkmcnt(0)
	buffer_inv sc1
	ds_read_b32 v2, v0
	s_add_i32 s4, 0, 0x20004
	v_mov_b32_e32 v0, s4
	ds_read_b32 v0, v0
	s_waitcnt lgkmcnt(1)
	v_cmp_ne_u32_e32 vcc, 0, v2
	s_cbranch_vccnz .LBB0_1999
	s_add_u32 s8, s68, 0x23718200
	s_addc_u32 s9, s69, 0
	s_add_u32 s10, s68, 0x23718400
	s_addc_u32 s11, s69, 0
	s_add_u32 s12, s68, 0x23718500
	s_addc_u32 s13, s69, 0
	s_add_u32 s14, s68, 0x23718600
	s_addc_u32 s15, s69, 0
	s_add_u32 s16, s68, 0x23718700
	s_addc_u32 s17, s69, 0
	s_add_u32 s18, s68, 0x23718800
	s_addc_u32 s19, s69, 0
	s_add_u32 s20, s68, 0x23718900
	s_addc_u32 s21, s69, 0
	s_add_u32 s22, s68, 0x23718a00
	s_addc_u32 s23, s69, 0
	s_add_u32 s24, s68, 0x23718b00
	s_addc_u32 s25, s69, 0
	s_add_u32 s26, s68, 0x23718c00
	s_addc_u32 s27, s69, 0
	s_add_u32 s28, s68, 0x23718d00
	s_addc_u32 s29, s69, 0
	s_add_u32 s30, s68, 0x23718e00
	s_addc_u32 s31, s69, 0
	s_add_u32 s34, s68, 0x23718f00
	s_addc_u32 s35, s69, 0
	s_add_u32 s36, s68, 0x23719000
	s_load_dword s4, s[0:1], 0x110
	s_addc_u32 s37, s69, 0
	s_add_u32 s38, s68, 0x23719100
	s_addc_u32 s39, s69, 0
	s_add_u32 s40, s68, 0x23719200
	s_addc_u32 s41, s69, 0
	s_waitcnt lgkmcnt(0)
	s_mul_i32 s4, s65, s4
	s_add_u32 s42, s68, 0x23719300
	s_mul_i32 s3, s4, s3
	s_addc_u32 s43, s69, 0
	s_mov_b32 s50, 1
	v_mov_b32_e32 v16, 0
	s_branch .LBB0_1987

.LBB0_2060:
	s_cmp_lt_i32 s67, 27
	s_cbranch_scc1 .LBB0_2114
	s_waitcnt vmcnt(0)
	v_readlane_b32 s4, v232, 0
	v_readlane_b32 s5, v232, 1
	s_waitcnt vmcnt(0)
	s_barrier
	s_and_saveexec_b64 s[6:7], s[4:5]
	s_cbranch_execz .LBB0_2113
	s_add_i32 s3, 0, 0x20000
	v_mov_b32_e32 v0, s3
	s_waitcnt vmcnt(0) expcnt(0) lgkmcnt(0)
	buffer_inv sc1
	ds_read_b32 v2, v0
	s_add_i32 s3, 0, 0x20004
	v_mov_b32_e32 v0, s3
	ds_read_b32 v0, v0
	s_waitcnt lgkmcnt(1)
	v_cmp_ne_u32_e32 vcc, 0, v2
	s_cbranch_vccnz .LBB0_2077
	s_add_u32 s8, s68, 0x23718200
	s_addc_u32 s9, s69, 0
	s_add_u32 s10, s68, 0x23718400
	s_addc_u32 s11, s69, 0
	s_add_u32 s12, s68, 0x23718500
	s_addc_u32 s13, s69, 0
	s_add_u32 s14, s68, 0x23718600
	s_addc_u32 s15, s69, 0
	s_add_u32 s16, s68, 0x23718700
	s_addc_u32 s17, s69, 0
	s_add_u32 s18, s68, 0x23718800
	s_addc_u32 s19, s69, 0
	s_add_u32 s20, s68, 0x23718900
	s_addc_u32 s21, s69, 0
	s_add_u32 s22, s68, 0x23718a00
	s_addc_u32 s23, s69, 0
	s_add_u32 s24, s68, 0x23718b00
	s_addc_u32 s25, s69, 0
	s_add_u32 s26, s68, 0x23718c00
	s_addc_u32 s27, s69, 0
	s_add_u32 s28, s68, 0x23718d00
	s_addc_u32 s29, s69, 0
	s_add_u32 s30, s68, 0x23718e00
	s_addc_u32 s31, s69, 0
	s_add_u32 s34, s68, 0x23718f00
	s_addc_u32 s35, s69, 0
	s_add_u32 s36, s68, 0x23719000
	s_load_dword s3, s[0:1], 0x110
	s_addc_u32 s37, s69, 0
	s_add_u32 s38, s68, 0x23719100
	s_addc_u32 s39, s69, 0
	s_add_u32 s40, s68, 0x23719200
	s_addc_u32 s41, s69, 0
	s_waitcnt lgkmcnt(0)
	s_mul_i32 s3, s65, s3
	s_add_u32 s42, s68, 0x23719300
	s_mul_i32 s3, s3, s64
	s_addc_u32 s43, s69, 0
	s_mov_b32 s50, 1
	v_mov_b32_e32 v16, 0
	s_branch .LBB0_2065

.LBB0_2120:
	s_or_b64 exec, exec, s[6:7]
	s_cmp_lt_i32 s67, 28
	s_cbranch_scc1 .LBB0_2174
	s_waitcnt vmcnt(0)
	v_readlane_b32 s4, v232, 0
	v_readlane_b32 s5, v232, 1
	s_waitcnt vmcnt(0)
	s_barrier
	s_and_saveexec_b64 s[6:7], s[4:5]
	s_cbranch_execz .LBB0_2173
	s_add_i32 s4, 0, 0x20000
	v_mov_b32_e32 v0, s4
	s_waitcnt vmcnt(0) expcnt(0) lgkmcnt(0)
	buffer_inv sc1
	ds_read_b32 v2, v0
	s_add_i32 s4, 0, 0x20004
	v_mov_b32_e32 v0, s4
	ds_read_b32 v0, v0
	s_waitcnt lgkmcnt(1)
	v_cmp_ne_u32_e32 vcc, 0, v2
	s_cbranch_vccnz .LBB0_2137
	s_add_u32 s8, s68, 0x23718200
	s_addc_u32 s9, s69, 0
	s_add_u32 s10, s68, 0x23718400
	s_addc_u32 s11, s69, 0
	s_add_u32 s12, s68, 0x23718500
	s_addc_u32 s13, s69, 0
	s_add_u32 s14, s68, 0x23718600
	s_addc_u32 s15, s69, 0
	s_add_u32 s16, s68, 0x23718700
	s_addc_u32 s17, s69, 0
	s_add_u32 s18, s68, 0x23718800
	s_addc_u32 s19, s69, 0
	s_add_u32 s20, s68, 0x23718900
	s_addc_u32 s21, s69, 0
	s_add_u32 s22, s68, 0x23718a00
	s_addc_u32 s23, s69, 0
	s_add_u32 s24, s68, 0x23718b00
	s_addc_u32 s25, s69, 0
	s_add_u32 s26, s68, 0x23718c00
	s_addc_u32 s27, s69, 0
	s_add_u32 s28, s68, 0x23718d00
	s_addc_u32 s29, s69, 0
	s_add_u32 s30, s68, 0x23718e00
	s_addc_u32 s31, s69, 0
	s_add_u32 s34, s68, 0x23718f00
	s_addc_u32 s35, s69, 0
	s_add_u32 s36, s68, 0x23719000
	s_load_dword s4, s[0:1], 0x110
	s_addc_u32 s37, s69, 0
	s_add_u32 s38, s68, 0x23719100
	s_addc_u32 s39, s69, 0
	s_add_u32 s40, s68, 0x23719200
	s_addc_u32 s41, s69, 0
	s_waitcnt lgkmcnt(0)
	s_mul_i32 s4, s65, s4
	s_add_u32 s42, s68, 0x23719300
	s_mul_i32 s3, s4, s3
	s_addc_u32 s43, s69, 0
	s_mov_b32 s50, 1
	v_mov_b32_e32 v16, 0
	s_branch .LBB0_2125

.LBB0_2215:
	s_cmp_lt_i32 s67, 29
	s_cbranch_scc1 .LBB0_2269
	s_waitcnt vmcnt(0)
	v_readlane_b32 s4, v232, 0
	v_readlane_b32 s5, v232, 1
	s_waitcnt vmcnt(0)
	s_barrier
	s_and_saveexec_b64 s[6:7], s[4:5]
	s_cbranch_execz .LBB0_2268
	s_add_i32 s3, 0, 0x20000
	v_mov_b32_e32 v0, s3
	s_waitcnt vmcnt(0) expcnt(0) lgkmcnt(0)
	buffer_inv sc1
	ds_read_b32 v2, v0
	s_add_i32 s3, 0, 0x20004
	v_mov_b32_e32 v0, s3
	ds_read_b32 v0, v0
	s_waitcnt lgkmcnt(1)
	v_cmp_ne_u32_e32 vcc, 0, v2
	s_cbranch_vccnz .LBB0_2232
	s_add_u32 s8, s68, 0x23718200
	s_addc_u32 s9, s69, 0
	s_add_u32 s10, s68, 0x23718400
	s_addc_u32 s11, s69, 0
	s_add_u32 s12, s68, 0x23718500
	s_addc_u32 s13, s69, 0
	s_add_u32 s14, s68, 0x23718600
	s_addc_u32 s15, s69, 0
	s_add_u32 s16, s68, 0x23718700
	s_addc_u32 s17, s69, 0
	s_add_u32 s18, s68, 0x23718800
	s_addc_u32 s19, s69, 0
	s_add_u32 s20, s68, 0x23718900
	s_addc_u32 s21, s69, 0
	s_add_u32 s22, s68, 0x23718a00
	s_addc_u32 s23, s69, 0
	s_add_u32 s24, s68, 0x23718b00
	s_addc_u32 s25, s69, 0
	s_add_u32 s26, s68, 0x23718c00
	s_addc_u32 s27, s69, 0
	s_add_u32 s28, s68, 0x23718d00
	s_addc_u32 s29, s69, 0
	s_add_u32 s30, s68, 0x23718e00
	s_addc_u32 s31, s69, 0
	s_add_u32 s34, s68, 0x23718f00
	s_addc_u32 s35, s69, 0
	s_add_u32 s36, s68, 0x23719000
	s_load_dword s3, s[0:1], 0x110
	s_addc_u32 s37, s69, 0
	s_add_u32 s38, s68, 0x23719100
	s_addc_u32 s39, s69, 0
	s_add_u32 s40, s68, 0x23719200
	s_addc_u32 s41, s69, 0
	s_waitcnt lgkmcnt(0)
	s_mul_i32 s3, s65, s3
	s_add_u32 s42, s68, 0x23719300
	s_mul_i32 s3, s3, s64
	s_addc_u32 s43, s69, 0
	s_mov_b32 s50, 1
	v_mov_b32_e32 v16, 0
	s_branch .LBB0_2220

.LBB0_2338:
	s_cmp_lt_i32 s67, 30
	s_cbranch_scc1 .LBB0_2392
	s_waitcnt vmcnt(0)
	v_readlane_b32 s4, v232, 0
	v_readlane_b32 s5, v232, 1
	s_waitcnt vmcnt(0) lgkmcnt(0)
	s_barrier
	s_and_saveexec_b64 s[6:7], s[4:5]
	s_cbranch_execz .LBB0_2391
	s_add_i32 s3, 0, 0x20000
	v_mov_b32_e32 v0, s3
	s_waitcnt vmcnt(0) expcnt(0) lgkmcnt(0)
	buffer_inv sc1
	ds_read_b32 v2, v0
	s_add_i32 s3, 0, 0x20004
	v_mov_b32_e32 v0, s3
	ds_read_b32 v0, v0
	s_waitcnt lgkmcnt(1)
	v_cmp_ne_u32_e32 vcc, 0, v2
	s_cbranch_vccnz .LBB0_2355
	s_add_u32 s8, s68, 0x23718200
	s_addc_u32 s9, s69, 0
	s_add_u32 s10, s68, 0x23718400
	s_addc_u32 s11, s69, 0
	s_add_u32 s12, s68, 0x23718500
	s_addc_u32 s13, s69, 0
	s_add_u32 s14, s68, 0x23718600
	s_addc_u32 s15, s69, 0
	s_add_u32 s16, s68, 0x23718700
	s_addc_u32 s17, s69, 0
	s_add_u32 s18, s68, 0x23718800
	s_addc_u32 s19, s69, 0
	s_add_u32 s20, s68, 0x23718900
	s_addc_u32 s21, s69, 0
	s_add_u32 s22, s68, 0x23718a00
	s_addc_u32 s23, s69, 0
	s_add_u32 s24, s68, 0x23718b00
	s_addc_u32 s25, s69, 0
	s_add_u32 s26, s68, 0x23718c00
	s_addc_u32 s27, s69, 0
	s_add_u32 s28, s68, 0x23718d00
	s_addc_u32 s29, s69, 0
	s_add_u32 s30, s68, 0x23718e00
	s_addc_u32 s31, s69, 0
	s_add_u32 s34, s68, 0x23718f00
	s_addc_u32 s35, s69, 0
	s_add_u32 s36, s68, 0x23719000
	s_load_dword s3, s[0:1], 0x110
	s_addc_u32 s37, s69, 0
	s_add_u32 s38, s68, 0x23719100
	s_addc_u32 s39, s69, 0
	s_add_u32 s40, s68, 0x23719200
	s_addc_u32 s41, s69, 0
	s_waitcnt lgkmcnt(0)
	s_mul_i32 s3, s65, s3
	s_add_u32 s42, s68, 0x23719300
	s_mul_i32 s3, s3, s64
	s_addc_u32 s43, s69, 0
	s_mov_b32 s50, 1
	v_mov_b32_e32 v16, 0
	s_branch .LBB0_2343

.LBB0_2409:
	s_cmp_lt_i32 s67, 31
	s_cbranch_scc1 .LBB0_2463
	s_waitcnt vmcnt(0)
	v_readlane_b32 s4, v232, 0
	v_readlane_b32 s5, v232, 1
	s_waitcnt vmcnt(0) lgkmcnt(0)
	s_barrier
	s_and_saveexec_b64 s[6:7], s[4:5]
	s_cbranch_execz .LBB0_2462
	s_add_i32 s3, 0, 0x20000
	v_mov_b32_e32 v0, s3
	s_waitcnt vmcnt(0) expcnt(0) lgkmcnt(0)
	buffer_inv sc1
	ds_read_b32 v2, v0
	s_add_i32 s3, 0, 0x20004
	v_mov_b32_e32 v0, s3
	ds_read_b32 v0, v0
	s_waitcnt lgkmcnt(1)
	v_cmp_ne_u32_e32 vcc, 0, v2
	s_cbranch_vccnz .LBB0_2426
	s_add_u32 s8, s68, 0x23718200
	s_addc_u32 s9, s69, 0
	s_add_u32 s10, s68, 0x23718400
	s_addc_u32 s11, s69, 0
	s_add_u32 s12, s68, 0x23718500
	s_addc_u32 s13, s69, 0
	s_add_u32 s14, s68, 0x23718600
	s_addc_u32 s15, s69, 0
	s_add_u32 s16, s68, 0x23718700
	s_addc_u32 s17, s69, 0
	s_add_u32 s18, s68, 0x23718800
	s_addc_u32 s19, s69, 0
	s_add_u32 s20, s68, 0x23718900
	s_addc_u32 s21, s69, 0
	s_add_u32 s22, s68, 0x23718a00
	s_addc_u32 s23, s69, 0
	s_add_u32 s24, s68, 0x23718b00
	s_addc_u32 s25, s69, 0
	s_add_u32 s26, s68, 0x23718c00
	s_addc_u32 s27, s69, 0
	s_add_u32 s28, s68, 0x23718d00
	s_addc_u32 s29, s69, 0
	s_add_u32 s30, s68, 0x23718e00
	s_addc_u32 s31, s69, 0
	s_add_u32 s34, s68, 0x23718f00
	s_addc_u32 s35, s69, 0
	s_add_u32 s36, s68, 0x23719000
	s_load_dword s3, s[0:1], 0x110
	s_addc_u32 s37, s69, 0
	s_add_u32 s38, s68, 0x23719100
	s_addc_u32 s39, s69, 0
	s_add_u32 s40, s68, 0x23719200
	s_addc_u32 s41, s69, 0
	s_waitcnt lgkmcnt(0)
	s_mul_i32 s3, s65, s3
	s_add_u32 s42, s68, 0x23719300
	s_mul_i32 s3, s3, s64
	s_addc_u32 s43, s69, 0
	s_mov_b32 s50, 1
	v_mov_b32_e32 v16, 0
	s_branch .LBB0_2414

.LBB0_2469:
	s_or_b64 exec, exec, s[6:7]
	s_cmp_lt_i32 s67, 32
	s_cbranch_scc1 .LBB0_2523
	s_waitcnt vmcnt(0)
	v_readlane_b32 s4, v232, 0
	v_readlane_b32 s5, v232, 1
	s_waitcnt vmcnt(0)
	s_barrier
	s_and_saveexec_b64 s[6:7], s[4:5]
	s_cbranch_execz .LBB0_2522
	s_add_i32 s4, 0, 0x20000
	v_mov_b32_e32 v0, s4
	s_waitcnt vmcnt(0) expcnt(0) lgkmcnt(0)
	buffer_inv sc1
	ds_read_b32 v2, v0
	s_add_i32 s4, 0, 0x20004
	v_mov_b32_e32 v0, s4
	ds_read_b32 v0, v0
	s_waitcnt lgkmcnt(1)
	v_cmp_ne_u32_e32 vcc, 0, v2
	s_cbranch_vccnz .LBB0_2486
	s_add_u32 s8, s68, 0x23718200
	s_addc_u32 s9, s69, 0
	s_add_u32 s10, s68, 0x23718400
	s_addc_u32 s11, s69, 0
	s_add_u32 s12, s68, 0x23718500
	s_addc_u32 s13, s69, 0
	s_add_u32 s14, s68, 0x23718600
	s_addc_u32 s15, s69, 0
	s_add_u32 s16, s68, 0x23718700
	s_addc_u32 s17, s69, 0
	s_add_u32 s18, s68, 0x23718800
	s_addc_u32 s19, s69, 0
	s_add_u32 s20, s68, 0x23718900
	s_addc_u32 s21, s69, 0
	s_add_u32 s22, s68, 0x23718a00
	s_addc_u32 s23, s69, 0
	s_add_u32 s24, s68, 0x23718b00
	s_addc_u32 s25, s69, 0
	s_add_u32 s26, s68, 0x23718c00
	s_addc_u32 s27, s69, 0
	s_add_u32 s28, s68, 0x23718d00
	s_addc_u32 s29, s69, 0
	s_add_u32 s30, s68, 0x23718e00
	s_addc_u32 s31, s69, 0
	s_add_u32 s34, s68, 0x23718f00
	s_addc_u32 s35, s69, 0
	s_add_u32 s36, s68, 0x23719000
	s_load_dword s4, s[0:1], 0x110
	s_addc_u32 s37, s69, 0
	s_add_u32 s38, s68, 0x23719100
	s_addc_u32 s39, s69, 0
	s_add_u32 s40, s68, 0x23719200
	s_addc_u32 s41, s69, 0
	s_waitcnt lgkmcnt(0)
	s_mul_i32 s4, s65, s4
	s_add_u32 s42, s68, 0x23719300
	s_mul_i32 s3, s4, s3
	s_addc_u32 s43, s69, 0
	s_mov_b32 s50, 1
	v_mov_b32_e32 v16, 0
	s_branch .LBB0_2474

.LBB0_2540:
	s_cmp_lt_i32 s67, 33
	s_cbranch_scc1 .LBB0_2594
	s_waitcnt vmcnt(0)
	v_readlane_b32 s4, v232, 0
	v_readlane_b32 s5, v232, 1
	s_waitcnt vmcnt(0)
	s_barrier
	s_and_saveexec_b64 s[6:7], s[4:5]
	s_cbranch_execz .LBB0_2593
	s_add_i32 s4, 0, 0x20000
	v_mov_b32_e32 v0, s4
	s_waitcnt vmcnt(0) expcnt(0) lgkmcnt(0)
	buffer_inv sc1
	ds_read_b32 v2, v0
	s_add_i32 s4, 0, 0x20004
	v_mov_b32_e32 v0, s4
	ds_read_b32 v0, v0
	s_waitcnt lgkmcnt(1)
	v_cmp_ne_u32_e32 vcc, 0, v2
	s_cbranch_vccnz .LBB0_2557
	s_add_u32 s8, s68, 0x23718200
	s_addc_u32 s9, s69, 0
	s_add_u32 s10, s68, 0x23718400
	s_addc_u32 s11, s69, 0
	s_add_u32 s12, s68, 0x23718500
	s_addc_u32 s13, s69, 0
	s_add_u32 s14, s68, 0x23718600
	s_addc_u32 s15, s69, 0
	s_add_u32 s16, s68, 0x23718700
	s_addc_u32 s17, s69, 0
	s_add_u32 s18, s68, 0x23718800
	s_addc_u32 s19, s69, 0
	s_add_u32 s20, s68, 0x23718900
	s_addc_u32 s21, s69, 0
	s_add_u32 s22, s68, 0x23718a00
	s_addc_u32 s23, s69, 0
	s_add_u32 s24, s68, 0x23718b00
	s_addc_u32 s25, s69, 0
	s_add_u32 s26, s68, 0x23718c00
	s_addc_u32 s27, s69, 0
	s_add_u32 s28, s68, 0x23718d00
	s_addc_u32 s29, s69, 0
	s_add_u32 s30, s68, 0x23718e00
	s_addc_u32 s31, s69, 0
	s_add_u32 s34, s68, 0x23718f00
	s_addc_u32 s35, s69, 0
	s_add_u32 s36, s68, 0x23719000
	s_load_dword s4, s[0:1], 0x110
	s_addc_u32 s37, s69, 0
	s_add_u32 s38, s68, 0x23719100
	s_addc_u32 s39, s69, 0
	s_add_u32 s40, s68, 0x23719200
	s_addc_u32 s41, s69, 0
	s_waitcnt lgkmcnt(0)
	s_mul_i32 s4, s65, s4
	s_add_u32 s42, s68, 0x23719300
	s_mul_i32 s3, s4, s3
	s_addc_u32 s43, s69, 0
	s_mov_b32 s50, 1
	v_mov_b32_e32 v16, 0
	s_branch .LBB0_2545

.LBB0_2615:
	s_cmp_lt_i32 s67, 34
	s_cbranch_scc1 .LBB0_2669
	s_waitcnt vmcnt(0)
	v_readlane_b32 s4, v232, 0
	v_readlane_b32 s5, v232, 1
	s_waitcnt vmcnt(0) lgkmcnt(0)
	s_barrier
	s_and_saveexec_b64 s[6:7], s[4:5]
	s_cbranch_execz .LBB0_2668
	s_add_i32 s3, 0, 0x20000
	v_mov_b32_e32 v0, s3
	s_waitcnt vmcnt(0) expcnt(0) lgkmcnt(0)
	buffer_inv sc1
	ds_read_b32 v2, v0
	s_add_i32 s3, 0, 0x20004
	v_mov_b32_e32 v0, s3
	ds_read_b32 v0, v0
	s_waitcnt lgkmcnt(1)
	v_cmp_ne_u32_e32 vcc, 0, v2
	s_cbranch_vccnz .LBB0_2632
	s_add_u32 s8, s68, 0x23718200
	s_addc_u32 s9, s69, 0
	s_add_u32 s10, s68, 0x23718400
	s_addc_u32 s11, s69, 0
	s_add_u32 s12, s68, 0x23718500
	s_addc_u32 s13, s69, 0
	s_add_u32 s14, s68, 0x23718600
	s_addc_u32 s15, s69, 0
	s_add_u32 s16, s68, 0x23718700
	s_addc_u32 s17, s69, 0
	s_add_u32 s18, s68, 0x23718800
	s_addc_u32 s19, s69, 0
	s_add_u32 s20, s68, 0x23718900
	s_addc_u32 s21, s69, 0
	s_add_u32 s22, s68, 0x23718a00
	s_addc_u32 s23, s69, 0
	s_add_u32 s24, s68, 0x23718b00
	s_addc_u32 s25, s69, 0
	s_add_u32 s26, s68, 0x23718c00
	s_addc_u32 s27, s69, 0
	s_add_u32 s28, s68, 0x23718d00
	s_addc_u32 s29, s69, 0
	s_add_u32 s30, s68, 0x23718e00
	s_addc_u32 s31, s69, 0
	s_add_u32 s34, s68, 0x23718f00
	s_addc_u32 s35, s69, 0
	s_add_u32 s36, s68, 0x23719000
	s_load_dword s3, s[0:1], 0x110
	s_addc_u32 s37, s69, 0
	s_add_u32 s38, s68, 0x23719100
	s_addc_u32 s39, s69, 0
	s_add_u32 s40, s68, 0x23719200
	s_addc_u32 s41, s69, 0
	s_waitcnt lgkmcnt(0)
	s_mul_i32 s3, s65, s3
	s_add_u32 s42, s68, 0x23719300
	s_mul_i32 s3, s3, s64
	s_addc_u32 s43, s69, 0
	s_mov_b32 s50, 1
	v_mov_b32_e32 v16, 0
	s_branch .LBB0_2620

.LBB0_2675:
	s_or_b64 exec, exec, s[6:7]
	s_cmp_lt_i32 s67, 35
	s_cbranch_scc1 .LBB0_2729
	s_waitcnt vmcnt(0)
	v_readlane_b32 s4, v232, 0
	v_readlane_b32 s5, v232, 1
	s_waitcnt vmcnt(0)
	s_barrier
	s_and_saveexec_b64 s[6:7], s[4:5]
	s_cbranch_execz .LBB0_2728
	s_add_i32 s4, 0, 0x20000
	v_mov_b32_e32 v0, s4
	s_waitcnt vmcnt(0) expcnt(0) lgkmcnt(0)
	buffer_inv sc1
	ds_read_b32 v2, v0
	s_add_i32 s4, 0, 0x20004
	v_mov_b32_e32 v0, s4
	ds_read_b32 v0, v0
	s_waitcnt lgkmcnt(1)
	v_cmp_ne_u32_e32 vcc, 0, v2
	s_cbranch_vccnz .LBB0_2692
	s_add_u32 s8, s68, 0x23718200
	s_addc_u32 s9, s69, 0
	s_add_u32 s10, s68, 0x23718400
	s_addc_u32 s11, s69, 0
	s_add_u32 s12, s68, 0x23718500
	s_addc_u32 s13, s69, 0
	s_add_u32 s14, s68, 0x23718600
	s_addc_u32 s15, s69, 0
	s_add_u32 s16, s68, 0x23718700
	s_addc_u32 s17, s69, 0
	s_add_u32 s18, s68, 0x23718800
	s_addc_u32 s19, s69, 0
	s_add_u32 s20, s68, 0x23718900
	s_addc_u32 s21, s69, 0
	s_add_u32 s22, s68, 0x23718a00
	s_addc_u32 s23, s69, 0
	s_add_u32 s24, s68, 0x23718b00
	s_addc_u32 s25, s69, 0
	s_add_u32 s26, s68, 0x23718c00
	s_addc_u32 s27, s69, 0
	s_add_u32 s28, s68, 0x23718d00
	s_addc_u32 s29, s69, 0
	s_add_u32 s30, s68, 0x23718e00
	s_addc_u32 s31, s69, 0
	s_add_u32 s34, s68, 0x23718f00
	s_addc_u32 s35, s69, 0
	s_add_u32 s36, s68, 0x23719000
	s_load_dword s4, s[0:1], 0x110
	s_addc_u32 s37, s69, 0
	s_add_u32 s38, s68, 0x23719100
	s_addc_u32 s39, s69, 0
	s_add_u32 s40, s68, 0x23719200
	s_addc_u32 s41, s69, 0
	s_waitcnt lgkmcnt(0)
	s_mul_i32 s4, s65, s4
	s_add_u32 s42, s68, 0x23719300
	s_mul_i32 s3, s4, s3
	s_addc_u32 s43, s69, 0
	s_mov_b32 s50, 1
	v_mov_b32_e32 v16, 0
	s_branch .LBB0_2680

.LBB0_2746:
	s_cmp_lt_i32 s67, 36
	s_cbranch_scc1 .LBB0_2800
	s_waitcnt vmcnt(0)
	v_readlane_b32 s4, v232, 0
	v_readlane_b32 s5, v232, 1
	s_waitcnt vmcnt(0)
	s_barrier
	s_and_saveexec_b64 s[6:7], s[4:5]
	s_cbranch_execz .LBB0_2799
	s_add_i32 s4, 0, 0x20000
	v_mov_b32_e32 v0, s4
	s_waitcnt vmcnt(0) expcnt(0) lgkmcnt(0)
	buffer_inv sc1
	ds_read_b32 v2, v0
	s_add_i32 s4, 0, 0x20004
	v_mov_b32_e32 v0, s4
	ds_read_b32 v0, v0
	s_waitcnt lgkmcnt(1)
	v_cmp_ne_u32_e32 vcc, 0, v2
	s_cbranch_vccnz .LBB0_2763
	s_add_u32 s8, s68, 0x23718200
	s_addc_u32 s9, s69, 0
	s_add_u32 s10, s68, 0x23718400
	s_addc_u32 s11, s69, 0
	s_add_u32 s12, s68, 0x23718500
	s_addc_u32 s13, s69, 0
	s_add_u32 s14, s68, 0x23718600
	s_addc_u32 s15, s69, 0
	s_add_u32 s16, s68, 0x23718700
	s_addc_u32 s17, s69, 0
	s_add_u32 s18, s68, 0x23718800
	s_addc_u32 s19, s69, 0
	s_add_u32 s20, s68, 0x23718900
	s_addc_u32 s21, s69, 0
	s_add_u32 s22, s68, 0x23718a00
	s_addc_u32 s23, s69, 0
	s_add_u32 s24, s68, 0x23718b00
	s_addc_u32 s25, s69, 0
	s_add_u32 s26, s68, 0x23718c00
	s_addc_u32 s27, s69, 0
	s_add_u32 s28, s68, 0x23718d00
	s_addc_u32 s29, s69, 0
	s_add_u32 s30, s68, 0x23718e00
	s_addc_u32 s31, s69, 0
	s_add_u32 s34, s68, 0x23718f00
	s_addc_u32 s35, s69, 0
	s_add_u32 s36, s68, 0x23719000
	s_load_dword s4, s[0:1], 0x110
	s_addc_u32 s37, s69, 0
	s_add_u32 s38, s68, 0x23719100
	s_addc_u32 s39, s69, 0
	s_add_u32 s40, s68, 0x23719200
	s_addc_u32 s41, s69, 0
	s_waitcnt lgkmcnt(0)
	s_mul_i32 s4, s65, s4
	s_add_u32 s42, s68, 0x23719300
	s_mul_i32 s3, s4, s3
	s_addc_u32 s43, s69, 0
	s_mov_b32 s50, 1
	v_mov_b32_e32 v16, 0
	s_branch .LBB0_2751

.LBB0_2821:
	s_cmp_lt_i32 s67, 37
	s_cbranch_scc1 .LBB0_2875
	s_waitcnt vmcnt(0)
	v_readlane_b32 s4, v232, 0
	v_readlane_b32 s5, v232, 1
	s_waitcnt vmcnt(0) lgkmcnt(0)
	s_barrier
	s_and_saveexec_b64 s[6:7], s[4:5]
	s_cbranch_execz .LBB0_2874
	s_add_i32 s3, 0, 0x20000
	v_mov_b32_e32 v0, s3
	s_waitcnt vmcnt(0) expcnt(0) lgkmcnt(0)
	buffer_inv sc1
	ds_read_b32 v2, v0
	s_add_i32 s3, 0, 0x20004
	v_mov_b32_e32 v0, s3
	ds_read_b32 v0, v0
	s_waitcnt lgkmcnt(1)
	v_cmp_ne_u32_e32 vcc, 0, v2
	s_cbranch_vccnz .LBB0_2838
	s_add_u32 s8, s68, 0x23718200
	s_addc_u32 s9, s69, 0
	s_add_u32 s10, s68, 0x23718400
	s_addc_u32 s11, s69, 0
	s_add_u32 s12, s68, 0x23718500
	s_addc_u32 s13, s69, 0
	s_add_u32 s14, s68, 0x23718600
	s_addc_u32 s15, s69, 0
	s_add_u32 s16, s68, 0x23718700
	s_addc_u32 s17, s69, 0
	s_add_u32 s18, s68, 0x23718800
	s_addc_u32 s19, s69, 0
	s_add_u32 s20, s68, 0x23718900
	s_addc_u32 s21, s69, 0
	s_add_u32 s22, s68, 0x23718a00
	s_addc_u32 s23, s69, 0
	s_add_u32 s24, s68, 0x23718b00
	s_addc_u32 s25, s69, 0
	s_add_u32 s26, s68, 0x23718c00
	s_addc_u32 s27, s69, 0
	s_add_u32 s28, s68, 0x23718d00
	s_addc_u32 s29, s69, 0
	s_add_u32 s30, s68, 0x23718e00
	s_addc_u32 s31, s69, 0
	s_add_u32 s34, s68, 0x23718f00
	s_addc_u32 s35, s69, 0
	s_add_u32 s36, s68, 0x23719000
	s_load_dword s3, s[0:1], 0x110
	s_addc_u32 s37, s69, 0
	s_add_u32 s38, s68, 0x23719100
	s_addc_u32 s39, s69, 0
	s_add_u32 s40, s68, 0x23719200
	s_addc_u32 s41, s69, 0
	s_waitcnt lgkmcnt(0)
	s_mul_i32 s3, s65, s3
	s_add_u32 s42, s68, 0x23719300
	s_mul_i32 s3, s3, s64
	s_addc_u32 s43, s69, 0
	s_mov_b32 s50, 1
	v_mov_b32_e32 v16, 0
	s_branch .LBB0_2826

.LBB0_2881:
	s_or_b64 exec, exec, s[6:7]
	s_cmp_lt_i32 s67, 38
	s_cbranch_scc1 .LBB0_2935
	s_waitcnt vmcnt(0)
	v_readlane_b32 s4, v232, 0
	v_readlane_b32 s5, v232, 1
	s_waitcnt vmcnt(0)
	s_barrier
	s_and_saveexec_b64 s[6:7], s[4:5]
	s_cbranch_execz .LBB0_2934
	s_add_i32 s4, 0, 0x20000
	v_mov_b32_e32 v0, s4
	s_waitcnt vmcnt(0) expcnt(0) lgkmcnt(0)
	buffer_inv sc1
	ds_read_b32 v2, v0
	s_add_i32 s4, 0, 0x20004
	v_mov_b32_e32 v0, s4
	ds_read_b32 v0, v0
	s_waitcnt lgkmcnt(1)
	v_cmp_ne_u32_e32 vcc, 0, v2
	s_cbranch_vccnz .LBB0_2898
	s_add_u32 s8, s68, 0x23718200
	s_addc_u32 s9, s69, 0
	s_add_u32 s10, s68, 0x23718400
	s_addc_u32 s11, s69, 0
	s_add_u32 s12, s68, 0x23718500
	s_addc_u32 s13, s69, 0
	s_add_u32 s14, s68, 0x23718600
	s_addc_u32 s15, s69, 0
	s_add_u32 s16, s68, 0x23718700
	s_addc_u32 s17, s69, 0
	s_add_u32 s18, s68, 0x23718800
	s_addc_u32 s19, s69, 0
	s_add_u32 s20, s68, 0x23718900
	s_addc_u32 s21, s69, 0
	s_add_u32 s22, s68, 0x23718a00
	s_addc_u32 s23, s69, 0
	s_add_u32 s24, s68, 0x23718b00
	s_addc_u32 s25, s69, 0
	s_add_u32 s26, s68, 0x23718c00
	s_addc_u32 s27, s69, 0
	s_add_u32 s28, s68, 0x23718d00
	s_addc_u32 s29, s69, 0
	s_add_u32 s30, s68, 0x23718e00
	s_addc_u32 s31, s69, 0
	s_add_u32 s34, s68, 0x23718f00
	s_addc_u32 s35, s69, 0
	s_add_u32 s36, s68, 0x23719000
	s_load_dword s4, s[0:1], 0x110
	s_addc_u32 s37, s69, 0
	s_add_u32 s38, s68, 0x23719100
	s_addc_u32 s39, s69, 0
	s_add_u32 s40, s68, 0x23719200
	s_addc_u32 s41, s69, 0
	s_waitcnt lgkmcnt(0)
	s_mul_i32 s4, s65, s4
	s_add_u32 s42, s68, 0x23719300
	s_mul_i32 s3, s4, s3
	s_addc_u32 s43, s69, 0
	s_mov_b32 s50, 1
	v_mov_b32_e32 v16, 0
	s_branch .LBB0_2886

.LBB0_2984:
	s_cmp_lt_i32 s67, 39
	s_cbranch_scc1 .LBB0_3038
	s_waitcnt vmcnt(0)
	v_readlane_b32 s4, v232, 0
	v_readlane_b32 s5, v232, 1
	s_waitcnt vmcnt(0)
	s_barrier
	s_and_saveexec_b64 s[6:7], s[4:5]
	s_cbranch_execz .LBB0_3037
	s_add_i32 s3, 0, 0x20000
	v_mov_b32_e32 v0, s3
	s_waitcnt vmcnt(0) expcnt(0) lgkmcnt(0)
	buffer_inv sc1
	ds_read_b32 v2, v0
	s_add_i32 s3, 0, 0x20004
	v_mov_b32_e32 v0, s3
	ds_read_b32 v0, v0
	s_waitcnt lgkmcnt(1)
	v_cmp_ne_u32_e32 vcc, 0, v2
	s_cbranch_vccnz .LBB0_3001
	s_add_u32 s8, s68, 0x23718200
	s_addc_u32 s9, s69, 0
	s_add_u32 s10, s68, 0x23718400
	s_addc_u32 s11, s69, 0
	s_add_u32 s12, s68, 0x23718500
	s_addc_u32 s13, s69, 0
	s_add_u32 s14, s68, 0x23718600
	s_addc_u32 s15, s69, 0
	s_add_u32 s16, s68, 0x23718700
	s_addc_u32 s17, s69, 0
	s_add_u32 s18, s68, 0x23718800
	s_addc_u32 s19, s69, 0
	s_add_u32 s20, s68, 0x23718900
	s_addc_u32 s21, s69, 0
	s_add_u32 s22, s68, 0x23718a00
	s_addc_u32 s23, s69, 0
	s_add_u32 s24, s68, 0x23718b00
	s_addc_u32 s25, s69, 0
	s_add_u32 s26, s68, 0x23718c00
	s_addc_u32 s27, s69, 0
	s_add_u32 s28, s68, 0x23718d00
	s_addc_u32 s29, s69, 0
	s_add_u32 s30, s68, 0x23718e00
	s_addc_u32 s31, s69, 0
	s_add_u32 s34, s68, 0x23718f00
	s_addc_u32 s35, s69, 0
	s_add_u32 s36, s68, 0x23719000
	s_load_dword s3, s[0:1], 0x110
	s_addc_u32 s37, s69, 0
	s_add_u32 s38, s68, 0x23719100
	s_addc_u32 s39, s69, 0
	s_add_u32 s40, s68, 0x23719200
	s_addc_u32 s41, s69, 0
	s_waitcnt lgkmcnt(0)
	s_mul_i32 s3, s65, s3
	s_add_u32 s42, s68, 0x23719300
	s_mul_i32 s3, s3, s64
	s_addc_u32 s43, s69, 0
	s_mov_b32 s50, 1
	v_mov_b32_e32 v16, 0
	s_branch .LBB0_2989

.LBB0_3042:
	s_or_b64 exec, exec, s[6:7]
	s_cmp_lt_u32 s67, 40
	s_cbranch_scc1 .LBB0_3096
	s_waitcnt vmcnt(0)
	v_readlane_b32 s4, v232, 0
	v_readlane_b32 s5, v232, 1
	s_waitcnt vmcnt(0) lgkmcnt(0)
	s_barrier
	s_and_saveexec_b64 s[6:7], s[4:5]
	s_cbranch_execz .LBB0_3095
	s_add_i32 s3, 0, 0x20000
	v_mov_b32_e32 v0, s3
	s_waitcnt vmcnt(0) expcnt(0) lgkmcnt(0)
	buffer_inv sc1
	ds_read_b32 v2, v0
	s_add_i32 s3, 0, 0x20004
	v_mov_b32_e32 v0, s3
	ds_read_b32 v0, v0
	s_waitcnt lgkmcnt(1)
	v_cmp_ne_u32_e32 vcc, 0, v2
	s_cbranch_vccnz .LBB0_3059
	s_add_u32 s8, s68, 0x23718200
	s_addc_u32 s9, s69, 0
	s_add_u32 s10, s68, 0x23718400
	s_addc_u32 s11, s69, 0
	s_add_u32 s12, s68, 0x23718500
	s_addc_u32 s13, s69, 0
	s_add_u32 s14, s68, 0x23718600
	s_addc_u32 s15, s69, 0
	s_add_u32 s16, s68, 0x23718700
	s_addc_u32 s17, s69, 0
	s_add_u32 s18, s68, 0x23718800
	s_addc_u32 s19, s69, 0
	s_add_u32 s20, s68, 0x23718900
	s_addc_u32 s21, s69, 0
	s_add_u32 s22, s68, 0x23718a00
	s_addc_u32 s23, s69, 0
	s_add_u32 s24, s68, 0x23718b00
	s_addc_u32 s25, s69, 0
	s_add_u32 s26, s68, 0x23718c00
	s_addc_u32 s27, s69, 0
	s_add_u32 s28, s68, 0x23718d00
	s_addc_u32 s29, s69, 0
	s_add_u32 s30, s68, 0x23718e00
	s_addc_u32 s31, s69, 0
	s_add_u32 s34, s68, 0x23718f00
	s_addc_u32 s35, s69, 0
	s_add_u32 s36, s68, 0x23719000
	s_load_dword s3, s[0:1], 0x110
	s_addc_u32 s37, s69, 0
	s_add_u32 s38, s68, 0x23719100
	s_addc_u32 s39, s69, 0
	s_add_u32 s40, s68, 0x23719200
	s_addc_u32 s41, s69, 0
	s_waitcnt lgkmcnt(0)
	s_mul_i32 s3, s65, s3
	s_add_u32 s42, s68, 0x23719300
	s_mul_i32 s3, s3, s64
	s_addc_u32 s43, s69, 0
	s_mov_b32 s50, 1
	v_mov_b32_e32 v16, 0
	s_branch .LBB0_3047

.LBB0_3113:
	s_cmp_lt_i32 s67, 41
	s_cbranch_scc1 .LBB0_3167
	s_waitcnt vmcnt(0)
	v_readlane_b32 s4, v232, 0
	v_readlane_b32 s5, v232, 1
	s_waitcnt vmcnt(0) lgkmcnt(0)
	s_barrier
	s_and_saveexec_b64 s[6:7], s[4:5]
	s_cbranch_execz .LBB0_3166
	s_add_i32 s3, 0, 0x20000
	v_mov_b32_e32 v0, s3
	s_waitcnt vmcnt(0) expcnt(0) lgkmcnt(0)
	buffer_inv sc1
	ds_read_b32 v2, v0
	s_add_i32 s3, 0, 0x20004
	v_mov_b32_e32 v0, s3
	ds_read_b32 v0, v0
	s_waitcnt lgkmcnt(1)
	v_cmp_ne_u32_e32 vcc, 0, v2
	s_cbranch_vccnz .LBB0_3130
	s_add_u32 s8, s68, 0x23718200
	s_addc_u32 s9, s69, 0
	s_add_u32 s10, s68, 0x23718400
	s_addc_u32 s11, s69, 0
	s_add_u32 s12, s68, 0x23718500
	s_addc_u32 s13, s69, 0
	s_add_u32 s14, s68, 0x23718600
	s_addc_u32 s15, s69, 0
	s_add_u32 s16, s68, 0x23718700
	s_addc_u32 s17, s69, 0
	s_add_u32 s18, s68, 0x23718800
	s_addc_u32 s19, s69, 0
	s_add_u32 s20, s68, 0x23718900
	s_addc_u32 s21, s69, 0
	s_add_u32 s22, s68, 0x23718a00
	s_addc_u32 s23, s69, 0
	s_add_u32 s24, s68, 0x23718b00
	s_addc_u32 s25, s69, 0
	s_add_u32 s26, s68, 0x23718c00
	s_addc_u32 s27, s69, 0
	s_add_u32 s28, s68, 0x23718d00
	s_addc_u32 s29, s69, 0
	s_add_u32 s30, s68, 0x23718e00
	s_addc_u32 s31, s69, 0
	s_add_u32 s34, s68, 0x23718f00
	s_addc_u32 s35, s69, 0
	s_add_u32 s36, s68, 0x23719000
	s_load_dword s3, s[0:1], 0x110
	s_addc_u32 s37, s69, 0
	s_add_u32 s38, s68, 0x23719100
	s_addc_u32 s39, s69, 0
	s_add_u32 s40, s68, 0x23719200
	s_addc_u32 s41, s69, 0
	s_waitcnt lgkmcnt(0)
	s_mul_i32 s3, s65, s3
	s_add_u32 s42, s68, 0x23719300
	s_mul_i32 s3, s3, s64
	s_addc_u32 s43, s69, 0
	s_mov_b32 s50, 1
	v_mov_b32_e32 v16, 0
	s_branch .LBB0_3118

.LBB0_3173:
	s_or_b64 exec, exec, s[6:7]
	s_cmp_lt_i32 s67, 42
	s_cbranch_scc1 .LBB0_3227
	s_waitcnt vmcnt(0)
	v_readlane_b32 s4, v232, 0
	v_readlane_b32 s5, v232, 1
	s_waitcnt vmcnt(0)
	s_barrier
	s_and_saveexec_b64 s[6:7], s[4:5]
	s_cbranch_execz .LBB0_3226
	s_add_i32 s4, 0, 0x20000
	v_mov_b32_e32 v0, s4
	s_waitcnt vmcnt(0) expcnt(0) lgkmcnt(0)
	buffer_inv sc1
	ds_read_b32 v2, v0
	s_add_i32 s4, 0, 0x20004
	v_mov_b32_e32 v0, s4
	ds_read_b32 v0, v0
	s_waitcnt lgkmcnt(1)
	v_cmp_ne_u32_e32 vcc, 0, v2
	s_cbranch_vccnz .LBB0_3190
	s_add_u32 s8, s68, 0x23718200
	s_addc_u32 s9, s69, 0
	s_add_u32 s10, s68, 0x23718400
	s_addc_u32 s11, s69, 0
	s_add_u32 s12, s68, 0x23718500
	s_addc_u32 s13, s69, 0
	s_add_u32 s14, s68, 0x23718600
	s_addc_u32 s15, s69, 0
	s_add_u32 s16, s68, 0x23718700
	s_addc_u32 s17, s69, 0
	s_add_u32 s18, s68, 0x23718800
	s_addc_u32 s19, s69, 0
	s_add_u32 s20, s68, 0x23718900
	s_addc_u32 s21, s69, 0
	s_add_u32 s22, s68, 0x23718a00
	s_addc_u32 s23, s69, 0
	s_add_u32 s24, s68, 0x23718b00
	s_addc_u32 s25, s69, 0
	s_add_u32 s26, s68, 0x23718c00
	s_addc_u32 s27, s69, 0
	s_add_u32 s28, s68, 0x23718d00
	s_addc_u32 s29, s69, 0
	s_add_u32 s30, s68, 0x23718e00
	s_addc_u32 s31, s69, 0
	s_add_u32 s34, s68, 0x23718f00
	s_addc_u32 s35, s69, 0
	s_add_u32 s36, s68, 0x23719000
	s_load_dword s4, s[0:1], 0x110
	s_addc_u32 s37, s69, 0
	s_add_u32 s38, s68, 0x23719100
	s_addc_u32 s39, s69, 0
	s_add_u32 s40, s68, 0x23719200
	s_addc_u32 s41, s69, 0
	s_waitcnt lgkmcnt(0)
	s_mul_i32 s4, s65, s4
	s_add_u32 s42, s68, 0x23719300
	s_mul_i32 s3, s4, s3
	s_addc_u32 s43, s69, 0
	s_mov_b32 s50, 1
	v_mov_b32_e32 v16, 0
	s_branch .LBB0_3178

.LBB0_3244:
	s_cmp_lt_i32 s67, 43
	s_cbranch_scc1 .LBB0_3298
	s_waitcnt vmcnt(0)
	s_waitcnt vmcnt(0)
	s_barrier
	s_mov_b64 s[6:7], exec
	v_readlane_b32 s4, v232, 0
	v_readlane_b32 s5, v232, 1
	s_and_b64 s[4:5], s[6:7], s[4:5]
	s_mov_b64 exec, s[4:5]
	s_cbranch_execz .LBB0_3297
	s_add_i32 s4, 0, 0x20000
	v_mov_b32_e32 v0, s4
	s_waitcnt vmcnt(0) expcnt(0) lgkmcnt(0)
	buffer_inv sc1
	ds_read_b32 v2, v0
	s_add_i32 s4, 0, 0x20004
	v_mov_b32_e32 v0, s4
	ds_read_b32 v0, v0
	s_waitcnt lgkmcnt(1)
	v_cmp_ne_u32_e32 vcc, 0, v2
	s_cbranch_vccnz .LBB0_3261
	s_load_dword s4, s[0:1], 0x110
	s_mov_b32 s48, 1
	v_mov_b32_e32 v16, 0
	s_waitcnt lgkmcnt(0)
	s_mul_i32 s4, s65, s4
	s_mul_i32 s3, s4, s3
	s_add_u32 s4, s68, 0x23718200
	s_addc_u32 s5, s69, 0
	s_add_u32 s8, s68, 0x23718400
	s_addc_u32 s9, s69, 0
	s_add_u32 s10, s68, 0x23718500
	s_addc_u32 s11, s69, 0
	s_add_u32 s12, s68, 0x23718600
	s_addc_u32 s13, s69, 0
	s_add_u32 s14, s68, 0x23718700
	s_addc_u32 s15, s69, 0
	s_add_u32 s16, s68, 0x23718800
	s_addc_u32 s17, s69, 0
	s_add_u32 s18, s68, 0x23718900
	s_addc_u32 s19, s69, 0
	s_add_u32 s20, s68, 0x23718a00
	s_addc_u32 s21, s69, 0
	s_add_u32 s22, s68, 0x23718b00
	s_addc_u32 s23, s69, 0
	s_add_u32 s24, s68, 0x23718c00
	s_addc_u32 s25, s69, 0
	s_add_u32 s26, s68, 0x23718d00
	s_addc_u32 s27, s69, 0
	s_add_u32 s28, s68, 0x23718e00
	s_addc_u32 s29, s69, 0
	s_add_u32 s30, s68, 0x23718f00
	s_addc_u32 s31, s69, 0
	s_add_u32 s34, s68, 0x23719000
	s_addc_u32 s35, s69, 0
	s_add_u32 s36, s68, 0x23719100
	s_addc_u32 s37, s69, 0
	s_add_u32 s38, s68, 0x23719200
	s_addc_u32 s39, s69, 0
	s_add_u32 s40, s68, 0x23719300
	s_addc_u32 s41, s69, 0
	s_branch .LBB0_3249

.LBB0_3276:
	s_or_b64 exec, exec, s[10:11]
	s_waitcnt vmcnt(0)
	s_waitcnt vmcnt(0)
